# v019 + norm phases: the two out-of-range (clamped duplicate) rows of each wave's 3-row batch skip their split-K slab merge
# speedup vs baseline: 1.0120x; 1.0050x over previous
; template <int MODE>
; DI void norm_phase(const Args& a, const Frame& F, int nslab, float sscale, float* RSTD, const float* SSP) {
;     ...
;             else { const u32x2* src = (const u32x2*)(X + (size_t)rows[r] * DM);
; #pragma unroll
;                 for (int j = 0; j < 4; ++j) { const u32x2 w = src[F.lane + 64 * j]; v[r][j] = (f32x4){bflo(w.x), bfhi(w.x), bflo(w.y), bfhi(w.y)}; } } }
;         if (MODE != 1 && nslab > 0) {
; #pragma unroll
;             for (int r = 0; r < RB; ++r) if (rows[r] >= NP) {
; #pragma unroll
;                 for (int hb = 0; hb < 2; ++hb) {
;                     u32x2 t[4][4];
; #pragma unroll
;                     for (int s4 = 0; s4 < 4; ++s4) { const int s = hb * 4 + s4; const u32x2* sp = (const u32x2*)((const bf16*)SL + ((size_t)(s < nslab ? s : 0) * NS + (rows[r] - NP)) * DM);
; #pragma unroll
;                         for (int j = 0; j < 4; ++j) t[s4][j] = sp[F.lane + 64 * j]; }
; #pragma unroll
;                     for (int s4 = 0; s4 < 4; ++s4) { const float wsc = (hb * 4 + s4 < nslab) ? sscale : 0.f;
; #pragma unroll
;                         for (int j = 0; j < 4; ++j) v[r][j] = v[r][j] + (f32x4){bflo(t[s4][j].x), bfhi(t[s4][j].x), bflo(t[s4][j].y), bfhi(t[s4][j].y)} * wsc; }
.LBB0_221:
	s_waitcnt vmcnt(7)
	v_lshlrev_b32_e32 v36, 16, v32
	v_and_b32_e32 v37, 0xffff0000, v32
	v_lshlrev_b32_e32 v32, 16, v33
	v_and_b32_e32 v33, 0xffff0000, v33
	s_waitcnt vmcnt(6)
	v_lshlrev_b32_e32 v42, 16, v40
	v_and_b32_e32 v43, 0xffff0000, v40
	v_lshlrev_b32_e32 v40, 16, v41
	v_and_b32_e32 v41, 0xffff0000, v41
	s_waitcnt vmcnt(5)
	v_lshlrev_b32_e32 v46, 16, v44
	v_and_b32_e32 v47, 0xffff0000, v44
	v_lshlrev_b32_e32 v44, 16, v45
	v_and_b32_e32 v45, 0xffff0000, v45
	s_waitcnt vmcnt(4)
	v_lshlrev_b32_e32 v50, 16, v48
	v_and_b32_e32 v51, 0xffff0000, v48
	v_lshlrev_b32_e32 v48, 16, v49
	s_cmpk_lt_i32 s12, 0x4000
	v_and_b32_e32 v49, 0xffff0000, v49
	s_cbranch_scc1 .LBB0_223
	s_cmp_eq_u64 s[14:15], 0
	s_cbranch_scc1 .LBB0_223
	s_add_i32 s62, s12, 0xffffc000
	s_lshl_b64 s[4:5], s[62:63], 11
	s_add_u32 s4, s77, s4
	s_addc_u32 s5, s66, s5
	v_lshl_add_u64 v[52:53], v[160:161], 3, s[4:5]
	v_lshl_add_u64 v[54:55], v[52:53], 0, s[82:83]
	global_load_dwordx2 v[74:75], v[52:53], off
	global_load_dwordx2 v[72:73], v[52:53], off offset:512
	global_load_dwordx2 v[70:71], v[52:53], off offset:1024
	global_load_dwordx2 v[68:69], v[52:53], off offset:1536
	s_waitcnt lgkmcnt(2)
	global_load_dwordx2 v[66:67], v[54:55], off offset:512
	s_waitcnt lgkmcnt(0)
	global_load_dwordx2 v[62:63], v[54:55], off offset:1024
	global_load_dwordx2 v[64:65], v[54:55], off offset:1536
	v_add_co_u32_e32 v54, vcc, s33, v52
	s_mov_b32 s4, 0x800000
	s_nop 0
	v_addc_co_u32_e32 v55, vcc, 0, v53, vcc
	global_load_dwordx2 v[60:61], v[54:55], off
	v_add_co_u32_e32 v54, vcc, s4, v52
	s_mov_b64 s[4:5], 0x800000
	s_nop 0
	v_addc_co_u32_e32 v55, vcc, 0, v53, vcc
	global_load_dwordx2 v[58:59], v[54:55], off
	v_lshl_add_u64 v[76:77], v[52:53], 0, s[4:5]
	s_mov_b64 s[4:5], 0xc00000
	v_lshl_add_u64 v[78:79], v[52:53], 0, s[4:5]
	s_mov_b32 s4, 0xc00000
	global_load_dwordx2 v[56:57], v[76:77], off offset:512
	global_load_dwordx2 v[54:55], v[76:77], off offset:1024
	v_add_co_u32_e32 v80, vcc, s4, v52
	global_load_dwordx2 v[76:77], v[76:77], off offset:1536
	s_nop 0
	v_addc_co_u32_e32 v81, vcc, 0, v53, vcc
	global_load_dwordx2 v[82:83], v[78:79], off offset:512
	global_load_dwordx2 v[90:91], v[78:79], off offset:1024
	s_nop 0
	global_load_dwordx2 v[78:79], v[78:79], off offset:1536
	s_nop 0
	global_load_dwordx2 v[80:81], v[80:81], off
	s_mov_b32 s4, 0x1000000
	s_waitcnt vmcnt(15)
	v_lshlrev_b32_e32 v92, 16, v74
	v_and_b32_e32 v93, 0xffff0000, v74
	s_waitcnt vmcnt(13)
	v_lshlrev_b32_e32 v96, 16, v70
	v_and_b32_e32 v97, 0xffff0000, v70
	v_lshlrev_b32_e32 v70, 16, v71
	v_and_b32_e32 v71, 0xffff0000, v71
	v_lshlrev_b32_e32 v74, 16, v75
	v_and_b32_e32 v75, 0xffff0000, v75
	v_pk_fma_f32 v[44:45], v[70:71], 0.5, v[44:45] op_sel_hi:[1,0,1]
	s_waitcnt vmcnt(10)
	v_lshlrev_b32_e32 v70, 16, v62
	v_and_b32_e32 v71, 0xffff0000, v62
	v_lshlrev_b32_e32 v62, 16, v63
	v_and_b32_e32 v63, 0xffff0000, v63
	v_pk_fma_f32 v[32:33], v[74:75], 0.5, v[32:33] op_sel_hi:[1,0,1]
	v_pk_fma_f32 v[44:45], v[62:63], 0.5, v[44:45] op_sel_hi:[1,0,1]
	s_waitcnt vmcnt(8)
	v_lshlrev_b32_e32 v62, 16, v60
	v_and_b32_e32 v63, 0xffff0000, v60
	v_lshlrev_b32_e32 v60, 16, v61
	v_and_b32_e32 v61, 0xffff0000, v61
	v_lshlrev_b32_e32 v94, 16, v72
	v_and_b32_e32 v95, 0xffff0000, v72
	v_lshlrev_b32_e32 v72, 16, v73
	v_and_b32_e32 v73, 0xffff0000, v73
	v_lshlrev_b32_e32 v98, 16, v68
	v_and_b32_e32 v99, 0xffff0000, v68
	v_lshlrev_b32_e32 v68, 16, v69
	v_and_b32_e32 v69, 0xffff0000, v69
	v_pk_fma_f32 v[32:33], v[60:61], 0.5, v[32:33] op_sel_hi:[1,0,1]
	v_add_co_u32_e32 v60, vcc, s4, v52
	v_pk_fma_f32 v[36:37], v[92:93], 0.5, v[36:37] op_sel_hi:[1,0,1]
	v_pk_fma_f32 v[40:41], v[72:73], 0.5, v[40:41] op_sel_hi:[1,0,1]
	v_pk_fma_f32 v[48:49], v[68:69], 0.5, v[48:49] op_sel_hi:[1,0,1]
	v_lshlrev_b32_e32 v72, 16, v64
	v_and_b32_e32 v73, 0xffff0000, v64
	v_lshlrev_b32_e32 v64, 16, v65
	v_and_b32_e32 v65, 0xffff0000, v65
	v_addc_co_u32_e32 v61, vcc, 0, v53, vcc
	s_mov_b64 s[4:5], 0x1000000
	v_pk_fma_f32 v[42:43], v[94:95], 0.5, v[42:43] op_sel_hi:[1,0,1]
	v_lshlrev_b32_e32 v68, 16, v66
	v_and_b32_e32 v69, 0xffff0000, v66
	v_lshlrev_b32_e32 v66, 16, v67
	v_and_b32_e32 v67, 0xffff0000, v67
	v_pk_fma_f32 v[48:49], v[64:65], 0.5, v[48:49] op_sel_hi:[1,0,1]
	v_pk_fma_f32 v[36:37], v[62:63], 0.5, v[36:37] op_sel_hi:[1,0,1]
	global_load_dwordx2 v[60:61], v[60:61], off
	s_waitcnt vmcnt(8)
	v_lshlrev_b32_e32 v62, 16, v58
	v_and_b32_e32 v63, 0xffff0000, v58
	v_lshlrev_b32_e32 v58, 16, v59
	v_and_b32_e32 v59, 0xffff0000, v59
	v_lshl_add_u64 v[64:65], v[52:53], 0, s[4:5]
	v_pk_fma_f32 v[40:41], v[66:67], 0.5, v[40:41] op_sel_hi:[1,0,1]
	v_pk_fma_f32 v[42:43], v[68:69], 0.5, v[42:43] op_sel_hi:[1,0,1]
	global_load_dwordx2 v[66:67], v[64:65], off offset:512
	v_pk_fma_f32 v[32:33], v[58:59], 0.5, v[32:33] op_sel_hi:[1,0,1]
	s_waitcnt vmcnt(8)
	v_lshlrev_b32_e32 v58, 16, v56
	v_and_b32_e32 v59, 0xffff0000, v56
	s_mov_b32 s4, 0x1400000
	v_pk_fma_f32 v[46:47], v[96:97], 0.5, v[46:47] op_sel_hi:[1,0,1]
	v_pk_fma_f32 v[36:37], v[62:63], 0.5, v[36:37] op_sel_hi:[1,0,1]
	v_lshlrev_b32_e32 v56, 16, v57
	global_load_dwordx2 v[62:63], v[64:65], off offset:1024
	v_and_b32_e32 v57, 0xffff0000, v57
	v_pk_fma_f32 v[42:43], v[58:59], 0.5, v[42:43] op_sel_hi:[1,0,1]
	global_load_dwordx2 v[58:59], v[64:65], off offset:1536
	v_add_co_u32_e32 v64, vcc, s4, v52
	v_pk_fma_f32 v[46:47], v[70:71], 0.5, v[46:47] op_sel_hi:[1,0,1]
	v_pk_fma_f32 v[40:41], v[56:57], 0.5, v[40:41] op_sel_hi:[1,0,1]
	s_waitcnt vmcnt(9)
	v_lshlrev_b32_e32 v56, 16, v54
	v_and_b32_e32 v57, 0xffff0000, v54
	v_addc_co_u32_e32 v65, vcc, 0, v53, vcc
	s_mov_b64 s[4:5], 0x1400000
	s_waitcnt vmcnt(8)
; template <int MODE>
; DI void norm_phase(const Args& a, const Frame& F, int nslab, float sscale, float* RSTD, const float* SSP) {
;     ...
;                 for (int hb = 0; hb < 2; ++hb) {
;                     u32x2 t[4][4];
; #pragma unroll
;                     for (int s4 = 0; s4 < 4; ++s4) { const int s = hb * 4 + s4; const u32x2* sp = (const u32x2*)((const bf16*)SL + ((size_t)(s < nslab ? s : 0) * NS + (rows[r] - NP)) * DM);
; #pragma unroll
;                         for (int j = 0; j < 4; ++j) t[s4][j] = sp[F.lane + 64 * j]; }
; #pragma unroll
;                     for (int s4 = 0; s4 < 4; ++s4) { const float wsc = (hb * 4 + s4 < nslab) ? sscale : 0.f;
; #pragma unroll
;                         for (int j = 0; j < 4; ++j) v[r][j] = v[r][j] + (f32x4){bflo(t[s4][j].x), bfhi(t[s4][j].x), bflo(t[s4][j].y), bfhi(t[s4][j].y)} * wsc; }
	v_lshlrev_b32_e32 v70, 16, v77
	v_and_b32_e32 v71, 0xffff0000, v77
	v_pk_fma_f32 v[50:51], v[98:99], 0.5, v[50:51] op_sel_hi:[1,0,1]
	v_lshlrev_b32_e32 v54, 16, v55
	global_load_dwordx2 v[64:65], v[64:65], off
	v_and_b32_e32 v55, 0xffff0000, v55
	v_pk_fma_f32 v[46:47], v[56:57], 0.5, v[46:47] op_sel_hi:[1,0,1]
	v_lshl_add_u64 v[56:57], v[52:53], 0, s[4:5]
	v_pk_fma_f32 v[48:49], v[70:71], 0.5, v[48:49] op_sel_hi:[1,0,1]
	s_waitcnt vmcnt(5)
	v_lshlrev_b32_e32 v70, 16, v80
	v_and_b32_e32 v71, 0xffff0000, v80
	s_mov_b32 s4, 0x1800000
	v_pk_fma_f32 v[50:51], v[72:73], 0.5, v[50:51] op_sel_hi:[1,0,1]
	v_pk_fma_f32 v[44:45], v[54:55], 0.5, v[44:45] op_sel_hi:[1,0,1]
	v_lshlrev_b32_e32 v54, 16, v76
	global_load_dwordx2 v[68:69], v[56:57], off offset:512
	v_and_b32_e32 v55, 0xffff0000, v76
	v_pk_fma_f32 v[36:37], v[70:71], 0.5, v[36:37] op_sel_hi:[1,0,1]
	v_add_co_u32_e32 v70, vcc, s4, v52
	s_mov_b64 s[4:5], 0x1800000
	v_pk_fma_f32 v[50:51], v[54:55], 0.5, v[50:51] op_sel_hi:[1,0,1]
	global_load_dwordx2 v[54:55], v[56:57], off offset:1024
	v_addc_co_u32_e32 v71, vcc, 0, v53, vcc
	v_lshl_add_u64 v[76:77], v[52:53], 0, s[4:5]
	v_lshlrev_b32_e32 v72, 16, v81
	v_and_b32_e32 v73, 0xffff0000, v81
	global_load_dwordx2 v[70:71], v[70:71], off
	v_pk_fma_f32 v[32:33], v[72:73], 0.5, v[32:33] op_sel_hi:[1,0,1]
	global_load_dwordx2 v[80:81], v[76:77], off offset:512
	v_lshlrev_b32_e32 v72, 16, v82
	global_load_dwordx2 v[56:57], v[56:57], off offset:1536
	v_and_b32_e32 v73, 0xffff0000, v82
	v_lshlrev_b32_e32 v74, 16, v83
	v_and_b32_e32 v75, 0xffff0000, v83
	s_mov_b32 s4, 0x1c00000
	v_pk_fma_f32 v[40:41], v[74:75], 0.5, v[40:41] op_sel_hi:[1,0,1]
	v_pk_fma_f32 v[42:43], v[72:73], 0.5, v[42:43] op_sel_hi:[1,0,1]
	v_lshlrev_b32_e32 v72, 16, v90
	v_and_b32_e32 v73, 0xffff0000, v90
	v_lshlrev_b32_e32 v74, 16, v91
	global_load_dwordx2 v[82:83], v[76:77], off offset:1024
	v_and_b32_e32 v75, 0xffff0000, v91
	v_add_co_u32_e32 v90, vcc, s4, v52
	v_pk_fma_f32 v[44:45], v[74:75], 0.5, v[44:45] op_sel_hi:[1,0,1]
	global_load_dwordx2 v[74:75], v[76:77], off offset:1536
	v_addc_co_u32_e32 v91, vcc, 0, v53, vcc
	global_load_dwordx2 v[90:91], v[90:91], off
	s_mov_b64 s[4:5], 0x1c00000
	v_pk_fma_f32 v[46:47], v[72:73], 0.5, v[46:47] op_sel_hi:[1,0,1]
	v_lshlrev_b32_e32 v72, 16, v78
	v_and_b32_e32 v73, 0xffff0000, v78
	v_lshlrev_b32_e32 v76, 16, v79
	v_and_b32_e32 v77, 0xffff0000, v79
	v_lshl_add_u64 v[52:53], v[52:53], 0, s[4:5]
	v_pk_fma_f32 v[48:49], v[76:77], 0.5, v[48:49] op_sel_hi:[1,0,1]
	v_pk_fma_f32 v[50:51], v[72:73], 0.5, v[50:51] op_sel_hi:[1,0,1]
	global_load_dwordx2 v[72:73], v[52:53], off offset:512
	global_load_dwordx2 v[76:77], v[52:53], off offset:1024
	s_nop 0
	global_load_dwordx2 v[52:53], v[52:53], off offset:1536
	s_waitcnt vmcnt(15)
	v_lshlrev_b32_e32 v78, 16, v60
	v_and_b32_e32 v79, 0xffff0000, v60
	v_lshlrev_b32_e32 v60, 16, v61
	v_and_b32_e32 v61, 0xffff0000, v61
	v_pk_fma_f32 v[32:33], v[60:61], 0.5, v[32:33] op_sel_hi:[1,0,1]
	s_waitcnt vmcnt(14)
	v_lshlrev_b32_e32 v60, 16, v66
	v_and_b32_e32 v61, 0xffff0000, v66
	v_pk_fma_f32 v[42:43], v[60:61], 0.5, v[42:43] op_sel_hi:[1,0,1]
	s_waitcnt vmcnt(13)
	v_lshlrev_b32_e32 v60, 16, v62
	v_and_b32_e32 v61, 0xffff0000, v62
	v_pk_fma_f32 v[46:47], v[60:61], 0.5, v[46:47] op_sel_hi:[1,0,1]
	s_waitcnt vmcnt(12)
	v_lshlrev_b32_e32 v60, 16, v58
	v_and_b32_e32 v61, 0xffff0000, v58
	v_lshlrev_b32_e32 v58, 16, v59
	v_and_b32_e32 v59, 0xffff0000, v59
	v_pk_fma_f32 v[36:37], v[78:79], 0.5, v[36:37] op_sel_hi:[1,0,1]
	v_pk_fma_f32 v[48:49], v[58:59], 0.5, v[48:49] op_sel_hi:[1,0,1]
	v_lshlrev_b32_e32 v62, 16, v63
	v_and_b32_e32 v63, 0xffff0000, v63
	v_pk_fma_f32 v[44:45], v[62:63], 0.5, v[44:45] op_sel_hi:[1,0,1]
	v_pk_fma_f32 v[50:51], v[60:61], 0.5, v[50:51] op_sel_hi:[1,0,1]
	v_lshlrev_b32_e32 v66, 16, v67
	v_and_b32_e32 v67, 0xffff0000, v67
	s_waitcnt vmcnt(11)
	v_lshlrev_b32_e32 v58, 16, v64
	v_and_b32_e32 v59, 0xffff0000, v64
	v_pk_fma_f32 v[36:37], v[58:59], 0.5, v[36:37] op_sel_hi:[1,0,1]
	v_lshlrev_b32_e32 v60, 16, v65
	v_and_b32_e32 v61, 0xffff0000, v65
	v_pk_fma_f32 v[40:41], v[66:67], 0.5, v[40:41] op_sel_hi:[1,0,1]
	v_pk_fma_f32 v[32:33], v[60:61], 0.5, v[32:33] op_sel_hi:[1,0,1]
	s_waitcnt vmcnt(10)
	v_lshlrev_b32_e32 v58, 16, v68
	v_and_b32_e32 v59, 0xffff0000, v68
	v_pk_fma_f32 v[42:43], v[58:59], 0.5, v[42:43] op_sel_hi:[1,0,1]
	v_lshlrev_b32_e32 v60, 16, v69
	v_and_b32_e32 v61, 0xffff0000, v69
	v_pk_fma_f32 v[40:41], v[60:61], 0.5, v[40:41] op_sel_hi:[1,0,1]
	s_waitcnt vmcnt(9)
	v_lshlrev_b32_e32 v58, 16, v54
	v_and_b32_e32 v59, 0xffff0000, v54
	v_lshlrev_b32_e32 v54, 16, v55
	v_and_b32_e32 v55, 0xffff0000, v55
	v_pk_fma_f32 v[44:45], v[54:55], 0.5, v[44:45] op_sel_hi:[1,0,1]
	v_pk_fma_f32 v[46:47], v[58:59], 0.5, v[46:47] op_sel_hi:[1,0,1]
	s_waitcnt vmcnt(6)
	v_lshlrev_b32_e32 v54, 16, v56
	v_and_b32_e32 v55, 0xffff0000, v56
	v_lshlrev_b32_e32 v56, 16, v57
	v_and_b32_e32 v57, 0xffff0000, v57
	v_pk_fma_f32 v[50:51], v[54:55], 0.5, v[50:51] op_sel_hi:[1,0,1]
	v_lshlrev_b32_e32 v54, 16, v70
	v_and_b32_e32 v55, 0xffff0000, v70
	v_pk_fma_f32 v[48:49], v[56:57], 0.5, v[48:49] op_sel_hi:[1,0,1]
	v_lshlrev_b32_e32 v56, 16, v71
	v_and_b32_e32 v57, 0xffff0000, v71
	v_pk_fma_f32 v[36:37], v[54:55], 0.5, v[36:37] op_sel_hi:[1,0,1]
	v_lshlrev_b32_e32 v54, 16, v80
	v_and_b32_e32 v55, 0xffff0000, v80
	v_pk_fma_f32 v[32:33], v[56:57], 0.5, v[32:33] op_sel_hi:[1,0,1]
	v_lshlrev_b32_e32 v56, 16, v81
	v_and_b32_e32 v57, 0xffff0000, v81
	v_pk_fma_f32 v[42:43], v[54:55], 0.5, v[42:43] op_sel_hi:[1,0,1]
	s_waitcnt vmcnt(5)
; template <int MODE>
; DI void norm_phase(const Args& a, const Frame& F, int nslab, float sscale, float* RSTD, const float* SSP) {
;     ...
;         if (MODE != 1 && nslab > 0) {
; #pragma unroll
;             for (int r = 0; r < RB; ++r) if (rows[r] >= NP) {
; #pragma unroll
;                 for (int hb = 0; hb < 2; ++hb) {
;                     u32x2 t[4][4];
; #pragma unroll
;                     for (int s4 = 0; s4 < 4; ++s4) { const int s = hb * 4 + s4; const u32x2* sp = (const u32x2*)((const bf16*)SL + ((size_t)(s < nslab ? s : 0) * NS + (rows[r] - NP)) * DM);
; #pragma unroll
;                         for (int j = 0; j < 4; ++j) t[s4][j] = sp[F.lane + 64 * j]; }
; #pragma unroll
;                     for (int s4 = 0; s4 < 4; ++s4) { const float wsc = (hb * 4 + s4 < nslab) ? sscale : 0.f;
; #pragma unroll
;                         for (int j = 0; j < 4; ++j) v[r][j] = v[r][j] + (f32x4){bflo(t[s4][j].x), bfhi(t[s4][j].x), bflo(t[s4][j].y), bfhi(t[s4][j].y)} * wsc; }
	v_lshlrev_b32_e32 v54, 16, v82
	v_and_b32_e32 v55, 0xffff0000, v82
	v_pk_fma_f32 v[40:41], v[56:57], 0.5, v[40:41] op_sel_hi:[1,0,1]
	v_lshlrev_b32_e32 v56, 16, v83
	v_and_b32_e32 v57, 0xffff0000, v83
	v_pk_fma_f32 v[46:47], v[54:55], 0.5, v[46:47] op_sel_hi:[1,0,1]
	s_waitcnt vmcnt(4)
	v_lshlrev_b32_e32 v54, 16, v74
	v_and_b32_e32 v55, 0xffff0000, v74
	v_pk_fma_f32 v[44:45], v[56:57], 0.5, v[44:45] op_sel_hi:[1,0,1]
	v_lshlrev_b32_e32 v56, 16, v75
	v_and_b32_e32 v57, 0xffff0000, v75
	v_pk_fma_f32 v[50:51], v[54:55], 0.5, v[50:51] op_sel_hi:[1,0,1]
	s_waitcnt vmcnt(3)
	v_lshlrev_b32_e32 v54, 16, v90
	v_and_b32_e32 v55, 0xffff0000, v90
	v_pk_fma_f32 v[48:49], v[56:57], 0.5, v[48:49] op_sel_hi:[1,0,1]
	v_lshlrev_b32_e32 v56, 16, v91
	v_and_b32_e32 v57, 0xffff0000, v91
	v_pk_fma_f32 v[36:37], v[54:55], 0.5, v[36:37] op_sel_hi:[1,0,1]
	s_waitcnt vmcnt(2)
	v_lshlrev_b32_e32 v54, 16, v72
	v_and_b32_e32 v55, 0xffff0000, v72
	v_pk_fma_f32 v[32:33], v[56:57], 0.5, v[32:33] op_sel_hi:[1,0,1]
	v_lshlrev_b32_e32 v56, 16, v73
	v_and_b32_e32 v57, 0xffff0000, v73
	v_pk_fma_f32 v[42:43], v[54:55], 0.5, v[42:43] op_sel_hi:[1,0,1]
	s_waitcnt vmcnt(1)
	v_lshlrev_b32_e32 v54, 16, v76
	v_and_b32_e32 v55, 0xffff0000, v76
	v_pk_fma_f32 v[40:41], v[56:57], 0.5, v[40:41] op_sel_hi:[1,0,1]
	v_lshlrev_b32_e32 v56, 16, v77
	v_and_b32_e32 v57, 0xffff0000, v77
	v_pk_fma_f32 v[46:47], v[54:55], 0.5, v[46:47] op_sel_hi:[1,0,1]
	s_waitcnt vmcnt(0)
	v_lshlrev_b32_e32 v54, 16, v52
	v_and_b32_e32 v55, 0xffff0000, v52
	v_lshlrev_b32_e32 v52, 16, v53
	v_and_b32_e32 v53, 0xffff0000, v53
	v_pk_fma_f32 v[44:45], v[56:57], 0.5, v[44:45] op_sel_hi:[1,0,1]
	v_pk_fma_f32 v[48:49], v[52:53], 0.5, v[48:49] op_sel_hi:[1,0,1]
	v_pk_fma_f32 v[50:51], v[54:55], 0.5, v[50:51] op_sel_hi:[1,0,1]
.LBB0_223:
	s_waitcnt vmcnt(3)
	v_lshlrev_b32_e32 v52, 16, v38
	v_and_b32_e32 v53, 0xffff0000, v38
	v_lshlrev_b32_e32 v38, 16, v39
	v_and_b32_e32 v39, 0xffff0000, v39
	s_waitcnt vmcnt(2)
	v_lshlrev_b32_e32 v54, 16, v34
	v_and_b32_e32 v55, 0xffff0000, v34
	v_lshlrev_b32_e32 v34, 16, v35
	v_and_b32_e32 v35, 0xffff0000, v35
	s_waitcnt vmcnt(1)
	v_lshlrev_b32_e32 v56, 16, v30
	v_and_b32_e32 v57, 0xffff0000, v30
	v_lshlrev_b32_e32 v30, 16, v31
	v_and_b32_e32 v31, 0xffff0000, v31
	s_waitcnt vmcnt(0)
	v_lshlrev_b32_e32 v58, 16, v28
	v_and_b32_e32 v59, 0xffff0000, v28
	v_lshlrev_b32_e32 v28, 16, v29
	s_cmpk_lt_i32 s8, 0x4000
	v_and_b32_e32 v29, 0xffff0000, v29
	s_cbranch_scc1 .LBB0_225
	s_cmp_eq_u64 s[10:11], 0
	s_cbranch_scc1 .LBB0_225
	s_add_i32 s62, s8, 0xffffc000
	s_lshl_b64 s[4:5], s[62:63], 11
	s_add_u32 s4, s77, s4
	s_addc_u32 s5, s66, s5
	s_waitcnt lgkmcnt(0)
	v_lshl_add_u64 v[60:61], v[160:161], 3, s[4:5]
	s_waitcnt lgkmcnt(0)
	v_lshl_add_u64 v[62:63], v[60:61], 0, s[82:83]
	global_load_dwordx2 v[82:83], v[60:61], off
	global_load_dwordx2 v[80:81], v[60:61], off offset:512
	global_load_dwordx2 v[78:79], v[60:61], off offset:1024
	global_load_dwordx2 v[76:77], v[60:61], off offset:1536
	global_load_dwordx2 v[74:75], v[62:63], off offset:512
	global_load_dwordx2 v[70:71], v[62:63], off offset:1024
	global_load_dwordx2 v[72:73], v[62:63], off offset:1536
	v_add_co_u32_e32 v62, vcc, s33, v60
	s_mov_b32 s4, 0x800000
	s_nop 0
	v_addc_co_u32_e32 v63, vcc, 0, v61, vcc
	global_load_dwordx2 v[68:69], v[62:63], off
	v_add_co_u32_e32 v62, vcc, s4, v60
	s_mov_b64 s[4:5], 0x800000
	s_nop 0
	v_addc_co_u32_e32 v63, vcc, 0, v61, vcc
	global_load_dwordx2 v[66:67], v[62:63], off
	v_lshl_add_u64 v[90:91], v[60:61], 0, s[4:5]
	s_mov_b64 s[4:5], 0xc00000
	v_lshl_add_u64 v[92:93], v[60:61], 0, s[4:5]
	s_mov_b32 s4, 0xc00000
	global_load_dwordx2 v[64:65], v[90:91], off offset:512
	global_load_dwordx2 v[62:63], v[90:91], off offset:1024
	v_add_co_u32_e32 v94, vcc, s4, v60
	global_load_dwordx2 v[90:91], v[90:91], off offset:1536
	s_nop 0
	v_addc_co_u32_e32 v95, vcc, 0, v61, vcc
	global_load_dwordx2 v[96:97], v[92:93], off offset:512
	global_load_dwordx2 v[98:99], v[92:93], off offset:1024
	s_nop 0
	global_load_dwordx2 v[92:93], v[92:93], off offset:1536
	s_nop 0
	global_load_dwordx2 v[94:95], v[94:95], off
	s_mov_b32 s4, 0x1000000
	s_waitcnt vmcnt(15)
	v_lshlrev_b32_e32 v100, 16, v82
	v_and_b32_e32 v101, 0xffff0000, v82
	s_waitcnt vmcnt(13)
	v_lshlrev_b32_e32 v104, 16, v78
	v_and_b32_e32 v105, 0xffff0000, v78
	v_lshlrev_b32_e32 v78, 16, v79
	v_and_b32_e32 v79, 0xffff0000, v79
	v_lshlrev_b32_e32 v82, 16, v83
	v_and_b32_e32 v83, 0xffff0000, v83
	v_pk_fma_f32 v[30:31], v[78:79], 0.5, v[30:31] op_sel_hi:[1,0,1]
	s_waitcnt vmcnt(10)
	v_lshlrev_b32_e32 v78, 16, v70
	v_and_b32_e32 v79, 0xffff0000, v70
	v_lshlrev_b32_e32 v70, 16, v71
	v_and_b32_e32 v71, 0xffff0000, v71
	v_pk_fma_f32 v[38:39], v[82:83], 0.5, v[38:39] op_sel_hi:[1,0,1]
	v_pk_fma_f32 v[30:31], v[70:71], 0.5, v[30:31] op_sel_hi:[1,0,1]
	s_waitcnt vmcnt(8)
	v_lshlrev_b32_e32 v70, 16, v68
	v_and_b32_e32 v71, 0xffff0000, v68
	v_lshlrev_b32_e32 v68, 16, v69
	v_and_b32_e32 v69, 0xffff0000, v69
	v_lshlrev_b32_e32 v102, 16, v80
	v_and_b32_e32 v103, 0xffff0000, v80
	v_lshlrev_b32_e32 v80, 16, v81
	v_and_b32_e32 v81, 0xffff0000, v81
	v_lshlrev_b32_e32 v106, 16, v76
	v_and_b32_e32 v107, 0xffff0000, v76
	v_lshlrev_b32_e32 v76, 16, v77
	v_and_b32_e32 v77, 0xffff0000, v77
	v_pk_fma_f32 v[38:39], v[68:69], 0.5, v[38:39] op_sel_hi:[1,0,1]
	v_add_co_u32_e32 v68, vcc, s4, v60
	v_pk_fma_f32 v[52:53], v[100:101], 0.5, v[52:53] op_sel_hi:[1,0,1]
	v_pk_fma_f32 v[34:35], v[80:81], 0.5, v[34:35] op_sel_hi:[1,0,1]
	v_pk_fma_f32 v[28:29], v[76:77], 0.5, v[28:29] op_sel_hi:[1,0,1]
	v_lshlrev_b32_e32 v80, 16, v72
	v_and_b32_e32 v81, 0xffff0000, v72
	v_lshlrev_b32_e32 v72, 16, v73
	v_and_b32_e32 v73, 0xffff0000, v73
	v_addc_co_u32_e32 v69, vcc, 0, v61, vcc
	s_mov_b64 s[4:5], 0x1000000
	v_pk_fma_f32 v[54:55], v[102:103], 0.5, v[54:55] op_sel_hi:[1,0,1]
	v_lshlrev_b32_e32 v76, 16, v74
	v_and_b32_e32 v77, 0xffff0000, v74
	v_lshlrev_b32_e32 v74, 16, v75
	v_and_b32_e32 v75, 0xffff0000, v75
	v_pk_fma_f32 v[28:29], v[72:73], 0.5, v[28:29] op_sel_hi:[1,0,1]
	v_pk_fma_f32 v[52:53], v[70:71], 0.5, v[52:53] op_sel_hi:[1,0,1]
	global_load_dwordx2 v[68:69], v[68:69], off
	s_waitcnt vmcnt(8)
; template <int MODE>
; DI void norm_phase(const Args& a, const Frame& F, int nslab, float sscale, float* RSTD, const float* SSP) {
;     ...
;                 for (int hb = 0; hb < 2; ++hb) {
;                     u32x2 t[4][4];
; #pragma unroll
;                     for (int s4 = 0; s4 < 4; ++s4) { const int s = hb * 4 + s4; const u32x2* sp = (const u32x2*)((const bf16*)SL + ((size_t)(s < nslab ? s : 0) * NS + (rows[r] - NP)) * DM);
; #pragma unroll
;                         for (int j = 0; j < 4; ++j) t[s4][j] = sp[F.lane + 64 * j]; }
; #pragma unroll
;                     for (int s4 = 0; s4 < 4; ++s4) { const float wsc = (hb * 4 + s4 < nslab) ? sscale : 0.f;
; #pragma unroll
;                         for (int j = 0; j < 4; ++j) v[r][j] = v[r][j] + (f32x4){bflo(t[s4][j].x), bfhi(t[s4][j].x), bflo(t[s4][j].y), bfhi(t[s4][j].y)} * wsc; }
	v_lshlrev_b32_e32 v70, 16, v66
	v_and_b32_e32 v71, 0xffff0000, v66
	v_lshlrev_b32_e32 v66, 16, v67
	v_and_b32_e32 v67, 0xffff0000, v67
	v_lshl_add_u64 v[72:73], v[60:61], 0, s[4:5]
	v_pk_fma_f32 v[34:35], v[74:75], 0.5, v[34:35] op_sel_hi:[1,0,1]
	v_pk_fma_f32 v[54:55], v[76:77], 0.5, v[54:55] op_sel_hi:[1,0,1]
	global_load_dwordx2 v[74:75], v[72:73], off offset:512
	v_pk_fma_f32 v[38:39], v[66:67], 0.5, v[38:39] op_sel_hi:[1,0,1]
	s_waitcnt vmcnt(8)
	v_lshlrev_b32_e32 v66, 16, v64
	v_and_b32_e32 v67, 0xffff0000, v64
	s_mov_b32 s4, 0x1400000
	v_pk_fma_f32 v[56:57], v[104:105], 0.5, v[56:57] op_sel_hi:[1,0,1]
	v_pk_fma_f32 v[52:53], v[70:71], 0.5, v[52:53] op_sel_hi:[1,0,1]
	v_lshlrev_b32_e32 v64, 16, v65
	global_load_dwordx2 v[70:71], v[72:73], off offset:1024
	v_and_b32_e32 v65, 0xffff0000, v65
	v_pk_fma_f32 v[54:55], v[66:67], 0.5, v[54:55] op_sel_hi:[1,0,1]
	global_load_dwordx2 v[66:67], v[72:73], off offset:1536
	v_add_co_u32_e32 v72, vcc, s4, v60
	v_pk_fma_f32 v[56:57], v[78:79], 0.5, v[56:57] op_sel_hi:[1,0,1]
	v_pk_fma_f32 v[34:35], v[64:65], 0.5, v[34:35] op_sel_hi:[1,0,1]
	s_waitcnt vmcnt(9)
	v_lshlrev_b32_e32 v64, 16, v62
	v_and_b32_e32 v65, 0xffff0000, v62
	v_addc_co_u32_e32 v73, vcc, 0, v61, vcc
	s_mov_b64 s[4:5], 0x1400000
	s_waitcnt vmcnt(8)
	v_lshlrev_b32_e32 v78, 16, v91
	v_and_b32_e32 v79, 0xffff0000, v91
	v_pk_fma_f32 v[58:59], v[106:107], 0.5, v[58:59] op_sel_hi:[1,0,1]
	v_lshlrev_b32_e32 v62, 16, v63
	global_load_dwordx2 v[72:73], v[72:73], off
	v_and_b32_e32 v63, 0xffff0000, v63
	v_pk_fma_f32 v[56:57], v[64:65], 0.5, v[56:57] op_sel_hi:[1,0,1]
	v_lshl_add_u64 v[64:65], v[60:61], 0, s[4:5]
	v_pk_fma_f32 v[28:29], v[78:79], 0.5, v[28:29] op_sel_hi:[1,0,1]
	s_waitcnt vmcnt(5)
	v_lshlrev_b32_e32 v78, 16, v94
	v_and_b32_e32 v79, 0xffff0000, v94
	s_mov_b32 s4, 0x1800000
	v_pk_fma_f32 v[58:59], v[80:81], 0.5, v[58:59] op_sel_hi:[1,0,1]
	v_pk_fma_f32 v[30:31], v[62:63], 0.5, v[30:31] op_sel_hi:[1,0,1]
	v_lshlrev_b32_e32 v62, 16, v90
	global_load_dwordx2 v[76:77], v[64:65], off offset:512
	v_and_b32_e32 v63, 0xffff0000, v90
	v_pk_fma_f32 v[52:53], v[78:79], 0.5, v[52:53] op_sel_hi:[1,0,1]
	v_add_co_u32_e32 v78, vcc, s4, v60
	s_mov_b64 s[4:5], 0x1800000
	v_pk_fma_f32 v[58:59], v[62:63], 0.5, v[58:59] op_sel_hi:[1,0,1]
	global_load_dwordx2 v[62:63], v[64:65], off offset:1024
	v_addc_co_u32_e32 v79, vcc, 0, v61, vcc
	v_lshl_add_u64 v[90:91], v[60:61], 0, s[4:5]
	v_lshlrev_b32_e32 v80, 16, v95
	v_and_b32_e32 v81, 0xffff0000, v95
	global_load_dwordx2 v[78:79], v[78:79], off
	v_pk_fma_f32 v[38:39], v[80:81], 0.5, v[38:39] op_sel_hi:[1,0,1]
	global_load_dwordx2 v[94:95], v[90:91], off offset:512
	v_lshlrev_b32_e32 v80, 16, v96
	global_load_dwordx2 v[64:65], v[64:65], off offset:1536
	v_and_b32_e32 v81, 0xffff0000, v96
	v_lshlrev_b32_e32 v82, 16, v97
	v_and_b32_e32 v83, 0xffff0000, v97
	s_mov_b32 s4, 0x1c00000
	v_pk_fma_f32 v[34:35], v[82:83], 0.5, v[34:35] op_sel_hi:[1,0,1]
	v_pk_fma_f32 v[54:55], v[80:81], 0.5, v[54:55] op_sel_hi:[1,0,1]
	v_lshlrev_b32_e32 v80, 16, v98
	v_and_b32_e32 v81, 0xffff0000, v98
	v_lshlrev_b32_e32 v82, 16, v99
	global_load_dwordx2 v[96:97], v[90:91], off offset:1024
	v_and_b32_e32 v83, 0xffff0000, v99
	v_add_co_u32_e32 v98, vcc, s4, v60
	v_pk_fma_f32 v[30:31], v[82:83], 0.5, v[30:31] op_sel_hi:[1,0,1]
	global_load_dwordx2 v[82:83], v[90:91], off offset:1536
	v_addc_co_u32_e32 v99, vcc, 0, v61, vcc
	global_load_dwordx2 v[98:99], v[98:99], off
	s_mov_b64 s[4:5], 0x1c00000
	v_pk_fma_f32 v[56:57], v[80:81], 0.5, v[56:57] op_sel_hi:[1,0,1]
	v_lshlrev_b32_e32 v80, 16, v92
	v_and_b32_e32 v81, 0xffff0000, v92
	v_lshlrev_b32_e32 v90, 16, v93
	v_and_b32_e32 v91, 0xffff0000, v93
	v_lshl_add_u64 v[60:61], v[60:61], 0, s[4:5]
	v_pk_fma_f32 v[28:29], v[90:91], 0.5, v[28:29] op_sel_hi:[1,0,1]
	v_pk_fma_f32 v[58:59], v[80:81], 0.5, v[58:59] op_sel_hi:[1,0,1]
	global_load_dwordx2 v[80:81], v[60:61], off offset:512
	global_load_dwordx2 v[90:91], v[60:61], off offset:1024
	s_nop 0
	global_load_dwordx2 v[60:61], v[60:61], off offset:1536
	s_waitcnt vmcnt(15)
	v_lshlrev_b32_e32 v92, 16, v68
	v_and_b32_e32 v93, 0xffff0000, v68
	v_lshlrev_b32_e32 v68, 16, v69
	v_and_b32_e32 v69, 0xffff0000, v69
	v_pk_fma_f32 v[38:39], v[68:69], 0.5, v[38:39] op_sel_hi:[1,0,1]
	s_waitcnt vmcnt(14)
; template <int MODE>
; DI void norm_phase(const Args& a, const Frame& F, int nslab, float sscale, float* RSTD, const float* SSP) {
;     ...
;                 for (int hb = 0; hb < 2; ++hb) {
;                     u32x2 t[4][4];
; #pragma unroll
;                     for (int s4 = 0; s4 < 4; ++s4) { const int s = hb * 4 + s4; const u32x2* sp = (const u32x2*)((const bf16*)SL + ((size_t)(s < nslab ? s : 0) * NS + (rows[r] - NP)) * DM);
; #pragma unroll
;                         for (int j = 0; j < 4; ++j) t[s4][j] = sp[F.lane + 64 * j]; }
; #pragma unroll
;                     for (int s4 = 0; s4 < 4; ++s4) { const float wsc = (hb * 4 + s4 < nslab) ? sscale : 0.f;
; #pragma unroll
;                         for (int j = 0; j < 4; ++j) v[r][j] = v[r][j] + (f32x4){bflo(t[s4][j].x), bfhi(t[s4][j].x), bflo(t[s4][j].y), bfhi(t[s4][j].y)} * wsc; }
	v_lshlrev_b32_e32 v68, 16, v74
	v_and_b32_e32 v69, 0xffff0000, v74
	v_pk_fma_f32 v[54:55], v[68:69], 0.5, v[54:55] op_sel_hi:[1,0,1]
	s_waitcnt vmcnt(13)
	v_lshlrev_b32_e32 v68, 16, v70
	v_and_b32_e32 v69, 0xffff0000, v70
	v_pk_fma_f32 v[56:57], v[68:69], 0.5, v[56:57] op_sel_hi:[1,0,1]
	s_waitcnt vmcnt(12)
	v_lshlrev_b32_e32 v68, 16, v66
	v_and_b32_e32 v69, 0xffff0000, v66
	v_lshlrev_b32_e32 v66, 16, v67
	v_and_b32_e32 v67, 0xffff0000, v67
	v_pk_fma_f32 v[52:53], v[92:93], 0.5, v[52:53] op_sel_hi:[1,0,1]
	v_pk_fma_f32 v[28:29], v[66:67], 0.5, v[28:29] op_sel_hi:[1,0,1]
	v_lshlrev_b32_e32 v70, 16, v71
	v_and_b32_e32 v71, 0xffff0000, v71
	v_pk_fma_f32 v[30:31], v[70:71], 0.5, v[30:31] op_sel_hi:[1,0,1]
	v_pk_fma_f32 v[58:59], v[68:69], 0.5, v[58:59] op_sel_hi:[1,0,1]
	v_lshlrev_b32_e32 v74, 16, v75
	v_and_b32_e32 v75, 0xffff0000, v75
	s_waitcnt vmcnt(11)
	v_lshlrev_b32_e32 v66, 16, v72
	v_and_b32_e32 v67, 0xffff0000, v72
	v_pk_fma_f32 v[52:53], v[66:67], 0.5, v[52:53] op_sel_hi:[1,0,1]
	v_lshlrev_b32_e32 v68, 16, v73
	v_and_b32_e32 v69, 0xffff0000, v73
	v_pk_fma_f32 v[34:35], v[74:75], 0.5, v[34:35] op_sel_hi:[1,0,1]
	v_pk_fma_f32 v[38:39], v[68:69], 0.5, v[38:39] op_sel_hi:[1,0,1]
	s_waitcnt vmcnt(10)
	v_lshlrev_b32_e32 v66, 16, v76
	v_and_b32_e32 v67, 0xffff0000, v76
	v_pk_fma_f32 v[54:55], v[66:67], 0.5, v[54:55] op_sel_hi:[1,0,1]
	v_lshlrev_b32_e32 v68, 16, v77
	v_and_b32_e32 v69, 0xffff0000, v77
	v_pk_fma_f32 v[34:35], v[68:69], 0.5, v[34:35] op_sel_hi:[1,0,1]
	s_waitcnt vmcnt(9)
	v_lshlrev_b32_e32 v66, 16, v62
	v_and_b32_e32 v67, 0xffff0000, v62
	v_lshlrev_b32_e32 v62, 16, v63
	v_and_b32_e32 v63, 0xffff0000, v63
	v_pk_fma_f32 v[30:31], v[62:63], 0.5, v[30:31] op_sel_hi:[1,0,1]
	v_pk_fma_f32 v[56:57], v[66:67], 0.5, v[56:57] op_sel_hi:[1,0,1]
	s_waitcnt vmcnt(6)
	v_lshlrev_b32_e32 v62, 16, v64
	v_and_b32_e32 v63, 0xffff0000, v64
	v_lshlrev_b32_e32 v64, 16, v65
	v_and_b32_e32 v65, 0xffff0000, v65
	v_pk_fma_f32 v[58:59], v[62:63], 0.5, v[58:59] op_sel_hi:[1,0,1]
	v_lshlrev_b32_e32 v62, 16, v78
	v_and_b32_e32 v63, 0xffff0000, v78
	v_pk_fma_f32 v[28:29], v[64:65], 0.5, v[28:29] op_sel_hi:[1,0,1]
	v_lshlrev_b32_e32 v64, 16, v79
	v_and_b32_e32 v65, 0xffff0000, v79
	v_pk_fma_f32 v[52:53], v[62:63], 0.5, v[52:53] op_sel_hi:[1,0,1]
	v_lshlrev_b32_e32 v62, 16, v94
	v_and_b32_e32 v63, 0xffff0000, v94
	v_pk_fma_f32 v[38:39], v[64:65], 0.5, v[38:39] op_sel_hi:[1,0,1]
	v_lshlrev_b32_e32 v64, 16, v95
	v_and_b32_e32 v65, 0xffff0000, v95
	v_pk_fma_f32 v[54:55], v[62:63], 0.5, v[54:55] op_sel_hi:[1,0,1]
	s_waitcnt vmcnt(5)
	v_lshlrev_b32_e32 v62, 16, v96
	v_and_b32_e32 v63, 0xffff0000, v96
	v_pk_fma_f32 v[34:35], v[64:65], 0.5, v[34:35] op_sel_hi:[1,0,1]
	v_lshlrev_b32_e32 v64, 16, v97
	v_and_b32_e32 v65, 0xffff0000, v97
	v_pk_fma_f32 v[56:57], v[62:63], 0.5, v[56:57] op_sel_hi:[1,0,1]
	s_waitcnt vmcnt(4)
	v_lshlrev_b32_e32 v62, 16, v82
	v_and_b32_e32 v63, 0xffff0000, v82
	v_pk_fma_f32 v[30:31], v[64:65], 0.5, v[30:31] op_sel_hi:[1,0,1]
	v_lshlrev_b32_e32 v64, 16, v83
	v_and_b32_e32 v65, 0xffff0000, v83
	v_pk_fma_f32 v[58:59], v[62:63], 0.5, v[58:59] op_sel_hi:[1,0,1]
	s_waitcnt vmcnt(3)
	v_lshlrev_b32_e32 v62, 16, v98
	v_and_b32_e32 v63, 0xffff0000, v98
	v_pk_fma_f32 v[28:29], v[64:65], 0.5, v[28:29] op_sel_hi:[1,0,1]
	v_lshlrev_b32_e32 v64, 16, v99
	v_and_b32_e32 v65, 0xffff0000, v99
	v_pk_fma_f32 v[52:53], v[62:63], 0.5, v[52:53] op_sel_hi:[1,0,1]
	s_waitcnt vmcnt(2)
	v_lshlrev_b32_e32 v62, 16, v80
	v_and_b32_e32 v63, 0xffff0000, v80
	v_pk_fma_f32 v[38:39], v[64:65], 0.5, v[38:39] op_sel_hi:[1,0,1]
	v_lshlrev_b32_e32 v64, 16, v81
	v_and_b32_e32 v65, 0xffff0000, v81
	v_pk_fma_f32 v[54:55], v[62:63], 0.5, v[54:55] op_sel_hi:[1,0,1]
	s_waitcnt vmcnt(1)
	v_lshlrev_b32_e32 v62, 16, v90
	v_and_b32_e32 v63, 0xffff0000, v90
	v_pk_fma_f32 v[34:35], v[64:65], 0.5, v[34:35] op_sel_hi:[1,0,1]
	v_lshlrev_b32_e32 v64, 16, v91
	v_and_b32_e32 v65, 0xffff0000, v91
	v_pk_fma_f32 v[56:57], v[62:63], 0.5, v[56:57] op_sel_hi:[1,0,1]
	s_waitcnt vmcnt(0)
	v_lshlrev_b32_e32 v62, 16, v60
	v_and_b32_e32 v63, 0xffff0000, v60
	v_lshlrev_b32_e32 v60, 16, v61
	v_and_b32_e32 v61, 0xffff0000, v61
	v_pk_fma_f32 v[30:31], v[64:65], 0.5, v[30:31] op_sel_hi:[1,0,1]
	v_pk_fma_f32 v[28:29], v[60:61], 0.5, v[28:29] op_sel_hi:[1,0,1]
	v_pk_fma_f32 v[58:59], v[62:63], 0.5, v[58:59] op_sel_hi:[1,0,1]

; template <int MODE>
; DI void norm_phase(const Args& a, const Frame& F, int nslab, float sscale, float* RSTD, const float* SSP) {
;     ...
;         if (MODE != 1 && nslab > 0) {
; #pragma unroll
;             for (int r = 0; r < RB; ++r) if (rows[r] >= NP) {
; #pragma unroll
;                 for (int hb = 0; hb < 2; ++hb) {
;                     u32x2 t[4][4];
; #pragma unroll
;                     for (int s4 = 0; s4 < 4; ++s4) { const int s = hb * 4 + s4; const u32x2* sp = (const u32x2*)((const bf16*)SL + ((size_t)(s < nslab ? s : 0) * NS + (rows[r] - NP)) * DM);
; #pragma unroll
;                         for (int j = 0; j < 4; ++j) t[s4][j] = sp[F.lane + 64 * j]; }
; #pragma unroll
;                     for (int s4 = 0; s4 < 4; ++s4) { const float wsc = (hb * 4 + s4 < nslab) ? sscale : 0.f;
; #pragma unroll
;                         for (int j = 0; j < 4; ++j) v[r][j] = v[r][j] + (f32x4){bflo(t[s4][j].x), bfhi(t[s4][j].x), bflo(t[s4][j].y), bfhi(t[s4][j].y)} * wsc; }
.LBB0_504:
	s_waitcnt vmcnt(7)
	v_lshlrev_b32_e32 v38, 16, v36
	v_and_b32_e32 v39, 0xffff0000, v36
	v_lshlrev_b32_e32 v36, 16, v37
	v_and_b32_e32 v37, 0xffff0000, v37
	s_waitcnt vmcnt(6)
	v_lshlrev_b32_e32 v44, 16, v40
	v_and_b32_e32 v45, 0xffff0000, v40
	v_lshlrev_b32_e32 v40, 16, v41
	v_and_b32_e32 v41, 0xffff0000, v41
	s_waitcnt vmcnt(5)
	v_lshlrev_b32_e32 v50, 16, v46
	v_and_b32_e32 v51, 0xffff0000, v46
	v_lshlrev_b32_e32 v48, 16, v47
	v_and_b32_e32 v49, 0xffff0000, v47
	s_waitcnt vmcnt(4)
	v_lshlrev_b32_e32 v46, 16, v42
	v_and_b32_e32 v47, 0xffff0000, v42
	v_lshlrev_b32_e32 v42, 16, v43
	s_cmpk_lt_i32 s12, 0x4000
	v_and_b32_e32 v43, 0xffff0000, v43
	s_cbranch_scc1 .LBB0_506
	s_cmp_eq_u64 s[14:15], 0
	s_cbranch_scc1 .LBB0_506
	s_add_i32 s62, s12, 0xffffc000
	s_lshl_b64 s[4:5], s[62:63], 11
	s_add_u32 s4, s77, s4
	s_addc_u32 s5, s66, s5
	v_lshl_add_u64 v[52:53], v[160:161], 3, s[4:5]
	global_load_dwordx2 v[54:55], v[52:53], off
	global_load_dwordx2 v[56:57], v[52:53], off offset:512
	global_load_dwordx2 v[58:59], v[52:53], off offset:1024
	global_load_dwordx2 v[60:61], v[52:53], off offset:1536
	v_add_co_u32_e32 v64, vcc, s33, v52
	v_lshl_add_u64 v[62:63], v[52:53], 0, s[82:83]
	s_nop 0
	v_addc_co_u32_e32 v65, vcc, 0, v53, vcc
	global_load_dwordx2 v[64:65], v[64:65], off
	s_nop 0
	global_load_dwordx2 v[72:73], v[62:63], off offset:512
	global_load_dwordx2 v[74:75], v[62:63], off offset:1024
	s_nop 0
	global_load_dwordx2 v[62:63], v[62:63], off offset:1536
	s_mov_b64 s[4:5], 0x800000
	v_lshl_add_u64 v[76:77], v[52:53], 0, s[4:5]
	s_mov_b32 s4, 0x800000
	v_add_co_u32_e32 v78, vcc, s4, v52
	s_mov_b64 s[4:5], 0xc00000
	s_nop 0
	v_addc_co_u32_e32 v79, vcc, 0, v53, vcc
	global_load_dwordx2 v[78:79], v[78:79], off
	s_nop 0
	global_load_dwordx2 v[80:81], v[76:77], off offset:512
	global_load_dwordx2 v[82:83], v[76:77], off offset:1024
	s_nop 0
	global_load_dwordx2 v[76:77], v[76:77], off offset:1536
	v_lshl_add_u64 v[84:85], v[52:53], 0, s[4:5]
	s_mov_b32 s4, 0xc00000
	v_add_co_u32_e32 v86, vcc, s4, v52
	s_mov_b64 s[4:5], 0x1000000
	s_nop 0
	v_addc_co_u32_e32 v87, vcc, 0, v53, vcc
	global_load_dwordx2 v[86:87], v[86:87], off
	s_nop 0
	global_load_dwordx2 v[88:89], v[84:85], off offset:512
	global_load_dwordx2 v[90:91], v[84:85], off offset:1024
	s_nop 0
	global_load_dwordx2 v[84:85], v[84:85], off offset:1536
	s_waitcnt vmcnt(15)
	v_lshlrev_b32_e32 v92, 16, v54
	v_and_b32_e32 v93, 0xffff0000, v54
	v_lshlrev_b32_e32 v54, 16, v55
	v_and_b32_e32 v55, 0xffff0000, v55
	v_pk_fma_f32 v[36:37], v[54:55], 0.5, v[36:37] op_sel_hi:[1,0,1]
	s_waitcnt vmcnt(14)
	v_lshlrev_b32_e32 v54, 16, v56
	v_and_b32_e32 v55, 0xffff0000, v56
	v_lshlrev_b32_e32 v56, 16, v57
	v_and_b32_e32 v57, 0xffff0000, v57
	v_pk_fma_f32 v[40:41], v[56:57], 0.5, v[40:41] op_sel_hi:[1,0,1]
	s_waitcnt vmcnt(13)
	v_lshlrev_b32_e32 v56, 16, v59
	v_and_b32_e32 v57, 0xffff0000, v59
	v_pk_fma_f32 v[44:45], v[54:55], 0.5, v[44:45] op_sel_hi:[1,0,1]
	v_lshlrev_b32_e32 v54, 16, v58
	v_and_b32_e32 v55, 0xffff0000, v58
	v_pk_fma_f32 v[48:49], v[56:57], 0.5, v[48:49] op_sel_hi:[1,0,1]
	s_waitcnt vmcnt(12)
	v_lshlrev_b32_e32 v56, 16, v61
	v_and_b32_e32 v57, 0xffff0000, v61
	v_pk_fma_f32 v[50:51], v[54:55], 0.5, v[50:51] op_sel_hi:[1,0,1]
	v_lshlrev_b32_e32 v54, 16, v60
	v_and_b32_e32 v55, 0xffff0000, v60
	v_pk_fma_f32 v[42:43], v[56:57], 0.5, v[42:43] op_sel_hi:[1,0,1]
	s_waitcnt vmcnt(11)
	v_lshlrev_b32_e32 v56, 16, v65
	v_and_b32_e32 v57, 0xffff0000, v65
	v_pk_fma_f32 v[38:39], v[92:93], 0.5, v[38:39] op_sel_hi:[1,0,1]
	v_pk_fma_f32 v[46:47], v[54:55], 0.5, v[46:47] op_sel_hi:[1,0,1]
	v_lshlrev_b32_e32 v54, 16, v64
	v_and_b32_e32 v55, 0xffff0000, v64
	v_pk_fma_f32 v[36:37], v[56:57], 0.5, v[36:37] op_sel_hi:[1,0,1]
	s_waitcnt vmcnt(10)
	v_lshlrev_b32_e32 v56, 16, v73
	v_and_b32_e32 v57, 0xffff0000, v73
	v_pk_fma_f32 v[38:39], v[54:55], 0.5, v[38:39] op_sel_hi:[1,0,1]
	v_lshlrev_b32_e32 v54, 16, v72
	v_and_b32_e32 v55, 0xffff0000, v72
	v_pk_fma_f32 v[40:41], v[56:57], 0.5, v[40:41] op_sel_hi:[1,0,1]
	s_waitcnt vmcnt(9)
	v_lshlrev_b32_e32 v56, 16, v75
	v_and_b32_e32 v57, 0xffff0000, v75
	v_pk_fma_f32 v[44:45], v[54:55], 0.5, v[44:45] op_sel_hi:[1,0,1]
	v_lshlrev_b32_e32 v54, 16, v74
	v_and_b32_e32 v55, 0xffff0000, v74
	v_pk_fma_f32 v[48:49], v[56:57], 0.5, v[48:49] op_sel_hi:[1,0,1]
	s_waitcnt vmcnt(8)
	v_lshlrev_b32_e32 v56, 16, v63
	v_and_b32_e32 v57, 0xffff0000, v63
	v_pk_fma_f32 v[50:51], v[54:55], 0.5, v[50:51] op_sel_hi:[1,0,1]
	v_lshlrev_b32_e32 v54, 16, v62
	v_and_b32_e32 v55, 0xffff0000, v62
	v_pk_fma_f32 v[42:43], v[56:57], 0.5, v[42:43] op_sel_hi:[1,0,1]
	s_waitcnt vmcnt(7)
	v_lshlrev_b32_e32 v56, 16, v79
	v_and_b32_e32 v57, 0xffff0000, v79
	v_pk_fma_f32 v[46:47], v[54:55], 0.5, v[46:47] op_sel_hi:[1,0,1]
	v_lshlrev_b32_e32 v54, 16, v78
	v_and_b32_e32 v55, 0xffff0000, v78
	v_pk_fma_f32 v[36:37], v[56:57], 0.5, v[36:37] op_sel_hi:[1,0,1]
	s_waitcnt vmcnt(6)
	v_lshlrev_b32_e32 v56, 16, v81
	v_and_b32_e32 v57, 0xffff0000, v81
	v_pk_fma_f32 v[38:39], v[54:55], 0.5, v[38:39] op_sel_hi:[1,0,1]
	v_lshlrev_b32_e32 v54, 16, v80
	v_and_b32_e32 v55, 0xffff0000, v80
	v_pk_fma_f32 v[40:41], v[56:57], 0.5, v[40:41] op_sel_hi:[1,0,1]
	s_waitcnt vmcnt(5)
	v_lshlrev_b32_e32 v56, 16, v83
	v_and_b32_e32 v57, 0xffff0000, v83
	v_pk_fma_f32 v[44:45], v[54:55], 0.5, v[44:45] op_sel_hi:[1,0,1]
	v_lshlrev_b32_e32 v54, 16, v82
	v_and_b32_e32 v55, 0xffff0000, v82
	v_pk_fma_f32 v[56:57], v[56:57], 0.5, v[48:49] op_sel_hi:[1,0,1]
	s_waitcnt vmcnt(4)
	v_lshlrev_b32_e32 v48, 16, v76
	v_and_b32_e32 v49, 0xffff0000, v76
	v_pk_fma_f32 v[54:55], v[54:55], 0.5, v[50:51] op_sel_hi:[1,0,1]
	v_lshlrev_b32_e32 v50, 16, v77
	v_and_b32_e32 v51, 0xffff0000, v77
	v_pk_fma_f32 v[58:59], v[48:49], 0.5, v[46:47] op_sel_hi:[1,0,1]
	s_waitcnt vmcnt(3)
; template <int MODE>
; DI void norm_phase(const Args& a, const Frame& F, int nslab, float sscale, float* RSTD, const float* SSP) {
;     ...
;                 for (int hb = 0; hb < 2; ++hb) {
;                     u32x2 t[4][4];
; #pragma unroll
;                     for (int s4 = 0; s4 < 4; ++s4) { const int s = hb * 4 + s4; const u32x2* sp = (const u32x2*)((const bf16*)SL + ((size_t)(s < nslab ? s : 0) * NS + (rows[r] - NP)) * DM);
; #pragma unroll
;                         for (int j = 0; j < 4; ++j) t[s4][j] = sp[F.lane + 64 * j]; }
; #pragma unroll
;                     for (int s4 = 0; s4 < 4; ++s4) { const float wsc = (hb * 4 + s4 < nslab) ? sscale : 0.f;
; #pragma unroll
;                         for (int j = 0; j < 4; ++j) v[r][j] = v[r][j] + (f32x4){bflo(t[s4][j].x), bfhi(t[s4][j].x), bflo(t[s4][j].y), bfhi(t[s4][j].y)} * wsc; }
	v_lshlrev_b32_e32 v46, 16, v87
	v_and_b32_e32 v47, 0xffff0000, v87
	v_pk_fma_f32 v[60:61], v[50:51], 0.5, v[42:43] op_sel_hi:[1,0,1]
	v_lshlrev_b32_e32 v42, 16, v86
	v_and_b32_e32 v43, 0xffff0000, v86
	v_pk_fma_f32 v[46:47], v[46:47], 0.5, v[36:37] op_sel_hi:[1,0,1]
	s_waitcnt vmcnt(2)
	v_lshlrev_b32_e32 v36, 16, v88
	v_and_b32_e32 v37, 0xffff0000, v88
	v_pk_fma_f32 v[50:51], v[42:43], 0.5, v[38:39] op_sel_hi:[1,0,1]
	v_lshlrev_b32_e32 v38, 16, v89
	v_and_b32_e32 v39, 0xffff0000, v89
	v_pk_fma_f32 v[48:49], v[36:37], 0.5, v[44:45] op_sel_hi:[1,0,1]
	s_waitcnt vmcnt(1)
	v_lshlrev_b32_e32 v36, 16, v90
	v_and_b32_e32 v37, 0xffff0000, v90
	v_pk_fma_f32 v[42:43], v[38:39], 0.5, v[40:41] op_sel_hi:[1,0,1]
	v_lshlrev_b32_e32 v38, 16, v91
	v_and_b32_e32 v39, 0xffff0000, v91
	v_pk_fma_f32 v[44:45], v[36:37], 0.5, v[54:55] op_sel_hi:[1,0,1]
	v_lshl_add_u64 v[54:55], v[52:53], 0, s[4:5]
	s_mov_b32 s4, 0x1000000
	v_pk_fma_f32 v[38:39], v[38:39], 0.5, v[56:57] op_sel_hi:[1,0,1]
	v_add_co_u32_e32 v56, vcc, s4, v52
	s_waitcnt vmcnt(0)
	v_lshlrev_b32_e32 v40, 16, v84
	v_and_b32_e32 v41, 0xffff0000, v84
	v_lshlrev_b32_e32 v36, 16, v85
	v_and_b32_e32 v37, 0xffff0000, v85
	v_addc_co_u32_e32 v57, vcc, 0, v53, vcc
	v_pk_fma_f32 v[36:37], v[36:37], 0.5, v[60:61] op_sel_hi:[1,0,1]
	v_pk_fma_f32 v[40:41], v[40:41], 0.5, v[58:59] op_sel_hi:[1,0,1]
	global_load_dwordx2 v[56:57], v[56:57], off
	s_nop 0
	global_load_dwordx2 v[58:59], v[54:55], off offset:512
	global_load_dwordx2 v[60:61], v[54:55], off offset:1024
	s_nop 0
	global_load_dwordx2 v[54:55], v[54:55], off offset:1536
	s_mov_b64 s[4:5], 0x1400000
	v_lshl_add_u64 v[62:63], v[52:53], 0, s[4:5]
	s_mov_b32 s4, 0x1400000
	v_add_co_u32_e32 v64, vcc, s4, v52
	s_mov_b64 s[4:5], 0x1800000
	s_nop 0
	v_addc_co_u32_e32 v65, vcc, 0, v53, vcc
	global_load_dwordx2 v[64:65], v[64:65], off
	s_nop 0
	global_load_dwordx2 v[72:73], v[62:63], off offset:512
	global_load_dwordx2 v[74:75], v[62:63], off offset:1024
	s_nop 0
	global_load_dwordx2 v[62:63], v[62:63], off offset:1536
	v_lshl_add_u64 v[76:77], v[52:53], 0, s[4:5]
	s_mov_b32 s4, 0x1800000
	v_add_co_u32_e32 v78, vcc, s4, v52
	s_mov_b64 s[4:5], 0x1c00000
	s_nop 0
	v_addc_co_u32_e32 v79, vcc, 0, v53, vcc
	global_load_dwordx2 v[78:79], v[78:79], off
	s_nop 0
	global_load_dwordx2 v[80:81], v[76:77], off offset:512
	global_load_dwordx2 v[82:83], v[76:77], off offset:1024
	s_nop 0
	global_load_dwordx2 v[76:77], v[76:77], off offset:1536
	v_lshl_add_u64 v[84:85], v[52:53], 0, s[4:5]
	s_mov_b32 s4, 0x1c00000
	v_add_co_u32_e32 v52, vcc, s4, v52
	s_waitcnt vmcnt(11)
	v_lshlrev_b32_e32 v90, 16, v56
	v_addc_co_u32_e32 v53, vcc, 0, v53, vcc
	global_load_dwordx2 v[52:53], v[52:53], off
	s_nop 0
	global_load_dwordx2 v[86:87], v[84:85], off offset:512
	global_load_dwordx2 v[88:89], v[84:85], off offset:1024
	s_nop 0
	global_load_dwordx2 v[84:85], v[84:85], off offset:1536
	v_and_b32_e32 v91, 0xffff0000, v56
	v_lshlrev_b32_e32 v56, 16, v57
	v_and_b32_e32 v57, 0xffff0000, v57
	v_pk_fma_f32 v[46:47], v[56:57], 0.5, v[46:47] op_sel_hi:[1,0,1]
	s_waitcnt vmcnt(14)
	v_lshlrev_b32_e32 v56, 16, v58
	v_and_b32_e32 v57, 0xffff0000, v58
	v_pk_fma_f32 v[48:49], v[56:57], 0.5, v[48:49] op_sel_hi:[1,0,1]
	s_waitcnt vmcnt(13)
	v_lshlrev_b32_e32 v56, 16, v60
	v_and_b32_e32 v57, 0xffff0000, v60
	v_pk_fma_f32 v[44:45], v[56:57], 0.5, v[44:45] op_sel_hi:[1,0,1]
	s_waitcnt vmcnt(12)
	v_lshlrev_b32_e32 v56, 16, v54
	v_and_b32_e32 v57, 0xffff0000, v54
	v_lshlrev_b32_e32 v54, 16, v55
	v_and_b32_e32 v55, 0xffff0000, v55
	v_pk_fma_f32 v[50:51], v[90:91], 0.5, v[50:51] op_sel_hi:[1,0,1]
	v_lshlrev_b32_e32 v58, 16, v59
	v_and_b32_e32 v59, 0xffff0000, v59
	v_pk_fma_f32 v[40:41], v[56:57], 0.5, v[40:41] op_sel_hi:[1,0,1]
	v_pk_fma_f32 v[36:37], v[54:55], 0.5, v[36:37] op_sel_hi:[1,0,1]
	s_waitcnt vmcnt(11)
	v_lshlrev_b32_e32 v54, 16, v64
	v_and_b32_e32 v55, 0xffff0000, v64
	v_lshlrev_b32_e32 v56, 16, v65
	v_and_b32_e32 v57, 0xffff0000, v65
	v_pk_fma_f32 v[42:43], v[58:59], 0.5, v[42:43] op_sel_hi:[1,0,1]
	v_lshlrev_b32_e32 v58, 16, v61
	v_and_b32_e32 v59, 0xffff0000, v61
	v_pk_fma_f32 v[46:47], v[56:57], 0.5, v[46:47] op_sel_hi:[1,0,1]
	v_pk_fma_f32 v[50:51], v[54:55], 0.5, v[50:51] op_sel_hi:[1,0,1]
	s_waitcnt vmcnt(10)
	v_lshlrev_b32_e32 v54, 16, v72
	v_and_b32_e32 v55, 0xffff0000, v72
	v_lshlrev_b32_e32 v56, 16, v73
	v_and_b32_e32 v57, 0xffff0000, v73
	v_pk_fma_f32 v[38:39], v[58:59], 0.5, v[38:39] op_sel_hi:[1,0,1]
	v_pk_fma_f32 v[42:43], v[56:57], 0.5, v[42:43] op_sel_hi:[1,0,1]
	v_pk_fma_f32 v[48:49], v[54:55], 0.5, v[48:49] op_sel_hi:[1,0,1]
	s_waitcnt vmcnt(9)
	v_lshlrev_b32_e32 v54, 16, v74
	v_and_b32_e32 v55, 0xffff0000, v74
	v_lshlrev_b32_e32 v56, 16, v75
	v_and_b32_e32 v57, 0xffff0000, v75
	v_pk_fma_f32 v[38:39], v[56:57], 0.5, v[38:39] op_sel_hi:[1,0,1]
	v_pk_fma_f32 v[44:45], v[54:55], 0.5, v[44:45] op_sel_hi:[1,0,1]
	s_waitcnt vmcnt(8)
	v_lshlrev_b32_e32 v54, 16, v62
	v_and_b32_e32 v55, 0xffff0000, v62
	v_lshlrev_b32_e32 v56, 16, v63
	v_and_b32_e32 v57, 0xffff0000, v63
	v_pk_fma_f32 v[36:37], v[56:57], 0.5, v[36:37] op_sel_hi:[1,0,1]
	v_pk_fma_f32 v[40:41], v[54:55], 0.5, v[40:41] op_sel_hi:[1,0,1]
	s_waitcnt vmcnt(7)
	v_lshlrev_b32_e32 v54, 16, v78
	v_and_b32_e32 v55, 0xffff0000, v78
	v_lshlrev_b32_e32 v56, 16, v79
	v_and_b32_e32 v57, 0xffff0000, v79
	v_pk_fma_f32 v[50:51], v[54:55], 0.5, v[50:51] op_sel_hi:[1,0,1]
	v_pk_fma_f32 v[46:47], v[56:57], 0.5, v[46:47] op_sel_hi:[1,0,1]
	s_waitcnt vmcnt(6)
	v_lshlrev_b32_e32 v54, 16, v80
	v_and_b32_e32 v55, 0xffff0000, v80
	v_lshlrev_b32_e32 v56, 16, v81
	v_and_b32_e32 v57, 0xffff0000, v81
	v_pk_fma_f32 v[48:49], v[54:55], 0.5, v[48:49] op_sel_hi:[1,0,1]
	v_pk_fma_f32 v[42:43], v[56:57], 0.5, v[42:43] op_sel_hi:[1,0,1]
	s_waitcnt vmcnt(5)
; template <int MODE>
; DI void norm_phase(const Args& a, const Frame& F, int nslab, float sscale, float* RSTD, const float* SSP) {
;     ...
;         if (MODE != 1 && nslab > 0) {
; #pragma unroll
;             for (int r = 0; r < RB; ++r) if (rows[r] >= NP) {
; #pragma unroll
;                 for (int hb = 0; hb < 2; ++hb) {
;                     u32x2 t[4][4];
; #pragma unroll
;                     for (int s4 = 0; s4 < 4; ++s4) { const int s = hb * 4 + s4; const u32x2* sp = (const u32x2*)((const bf16*)SL + ((size_t)(s < nslab ? s : 0) * NS + (rows[r] - NP)) * DM);
; #pragma unroll
;                         for (int j = 0; j < 4; ++j) t[s4][j] = sp[F.lane + 64 * j]; }
; #pragma unroll
;                     for (int s4 = 0; s4 < 4; ++s4) { const float wsc = (hb * 4 + s4 < nslab) ? sscale : 0.f;
; #pragma unroll
;                         for (int j = 0; j < 4; ++j) v[r][j] = v[r][j] + (f32x4){bflo(t[s4][j].x), bfhi(t[s4][j].x), bflo(t[s4][j].y), bfhi(t[s4][j].y)} * wsc; }
	v_lshlrev_b32_e32 v54, 16, v82
	v_and_b32_e32 v55, 0xffff0000, v82
	v_lshlrev_b32_e32 v56, 16, v83
	v_and_b32_e32 v57, 0xffff0000, v83
	v_pk_fma_f32 v[54:55], v[54:55], 0.5, v[44:45] op_sel_hi:[1,0,1]
	v_pk_fma_f32 v[56:57], v[56:57], 0.5, v[38:39] op_sel_hi:[1,0,1]
	s_waitcnt vmcnt(4)
	v_lshlrev_b32_e32 v38, 16, v76
	v_and_b32_e32 v39, 0xffff0000, v76
	v_lshlrev_b32_e32 v44, 16, v77
	v_and_b32_e32 v45, 0xffff0000, v77
	v_pk_fma_f32 v[58:59], v[38:39], 0.5, v[40:41] op_sel_hi:[1,0,1]
	v_pk_fma_f32 v[60:61], v[44:45], 0.5, v[36:37] op_sel_hi:[1,0,1]
	s_waitcnt vmcnt(3)
	v_lshlrev_b32_e32 v36, 16, v53
	v_and_b32_e32 v37, 0xffff0000, v53
	s_waitcnt vmcnt(2)
	v_lshlrev_b32_e32 v40, 16, v87
	v_and_b32_e32 v41, 0xffff0000, v87
	v_lshlrev_b32_e32 v38, 16, v52
	v_and_b32_e32 v39, 0xffff0000, v52
	v_pk_fma_f32 v[36:37], v[36:37], 0.5, v[46:47] op_sel_hi:[1,0,1]
	v_lshlrev_b32_e32 v44, 16, v86
	v_and_b32_e32 v45, 0xffff0000, v86
	v_pk_fma_f32 v[40:41], v[40:41], 0.5, v[42:43] op_sel_hi:[1,0,1]
	s_waitcnt vmcnt(1)
	v_lshlrev_b32_e32 v42, 16, v88
	v_and_b32_e32 v43, 0xffff0000, v88
	v_lshlrev_b32_e32 v46, 16, v89
	v_and_b32_e32 v47, 0xffff0000, v89
	v_pk_fma_f32 v[38:39], v[38:39], 0.5, v[50:51] op_sel_hi:[1,0,1]
	v_pk_fma_f32 v[44:45], v[44:45], 0.5, v[48:49] op_sel_hi:[1,0,1]
	v_pk_fma_f32 v[48:49], v[46:47], 0.5, v[56:57] op_sel_hi:[1,0,1]
	v_pk_fma_f32 v[50:51], v[42:43], 0.5, v[54:55] op_sel_hi:[1,0,1]
	s_waitcnt vmcnt(0)
	v_lshlrev_b32_e32 v46, 16, v84
	v_and_b32_e32 v47, 0xffff0000, v84
	v_lshlrev_b32_e32 v42, 16, v85
	v_and_b32_e32 v43, 0xffff0000, v85
	v_pk_fma_f32 v[42:43], v[42:43], 0.5, v[60:61] op_sel_hi:[1,0,1]
	v_pk_fma_f32 v[46:47], v[46:47], 0.5, v[58:59] op_sel_hi:[1,0,1]
.LBB0_506:
	s_waitcnt vmcnt(3)
	v_lshlrev_b32_e32 v52, 16, v34
	v_and_b32_e32 v53, 0xffff0000, v34
	v_lshlrev_b32_e32 v34, 16, v35
	v_and_b32_e32 v35, 0xffff0000, v35
	s_waitcnt vmcnt(2)
	v_lshlrev_b32_e32 v54, 16, v32
	v_and_b32_e32 v55, 0xffff0000, v32
	v_lshlrev_b32_e32 v32, 16, v33
	v_and_b32_e32 v33, 0xffff0000, v33
	s_waitcnt vmcnt(1)
	v_lshlrev_b32_e32 v60, 16, v30
	v_and_b32_e32 v61, 0xffff0000, v30
	v_lshlrev_b32_e32 v58, 16, v31
	v_and_b32_e32 v59, 0xffff0000, v31
	s_waitcnt vmcnt(0)
	v_lshlrev_b32_e32 v56, 16, v28
	v_and_b32_e32 v57, 0xffff0000, v28
	v_lshlrev_b32_e32 v30, 16, v29
	s_cmpk_lt_i32 s8, 0x4000
	v_and_b32_e32 v31, 0xffff0000, v29
	s_cbranch_scc1 .LBB0_508
	s_cmp_eq_u64 s[10:11], 0
	s_cbranch_scc1 .LBB0_508
	s_add_i32 s62, s8, 0xffffc000
	s_lshl_b64 s[4:5], s[62:63], 11
	s_add_u32 s4, s77, s4
	s_addc_u32 s5, s66, s5
	v_lshl_add_u64 v[28:29], v[160:161], 3, s[4:5]
	global_load_dwordx2 v[62:63], v[28:29], off
	global_load_dwordx2 v[64:65], v[28:29], off offset:512
	global_load_dwordx2 v[72:73], v[28:29], off offset:1024
	global_load_dwordx2 v[74:75], v[28:29], off offset:1536
	v_add_co_u32_e32 v78, vcc, s33, v28
	v_lshl_add_u64 v[76:77], v[28:29], 0, s[82:83]
	s_nop 0
	v_addc_co_u32_e32 v79, vcc, 0, v29, vcc
	global_load_dwordx2 v[78:79], v[78:79], off
	s_nop 0
	global_load_dwordx2 v[80:81], v[76:77], off offset:512
	global_load_dwordx2 v[82:83], v[76:77], off offset:1024
	s_nop 0
	global_load_dwordx2 v[76:77], v[76:77], off offset:1536
	s_mov_b64 s[4:5], 0x800000
	v_lshl_add_u64 v[84:85], v[28:29], 0, s[4:5]
	s_mov_b32 s4, 0x800000
	v_add_co_u32_e32 v86, vcc, s4, v28
	s_mov_b64 s[4:5], 0xc00000
	s_nop 0
	v_addc_co_u32_e32 v87, vcc, 0, v29, vcc
	global_load_dwordx2 v[86:87], v[86:87], off
	s_nop 0
	global_load_dwordx2 v[88:89], v[84:85], off offset:512
	global_load_dwordx2 v[90:91], v[84:85], off offset:1024
	s_nop 0
	global_load_dwordx2 v[84:85], v[84:85], off offset:1536
	v_lshl_add_u64 v[92:93], v[28:29], 0, s[4:5]
	s_mov_b32 s4, 0xc00000
	v_add_co_u32_e32 v94, vcc, s4, v28
	s_mov_b64 s[4:5], 0x1000000
	s_nop 0
	v_addc_co_u32_e32 v95, vcc, 0, v29, vcc
	global_load_dwordx2 v[94:95], v[94:95], off
	s_nop 0
	global_load_dwordx2 v[96:97], v[92:93], off offset:512
	global_load_dwordx2 v[98:99], v[92:93], off offset:1024
	s_nop 0
	global_load_dwordx2 v[92:93], v[92:93], off offset:1536
	s_waitcnt vmcnt(15)
	v_lshlrev_b32_e32 v100, 16, v62
	v_and_b32_e32 v101, 0xffff0000, v62
	v_lshlrev_b32_e32 v62, 16, v63
	v_and_b32_e32 v63, 0xffff0000, v63
	v_pk_fma_f32 v[34:35], v[62:63], 0.5, v[34:35] op_sel_hi:[1,0,1]
	s_waitcnt vmcnt(14)
	v_lshlrev_b32_e32 v62, 16, v64
	v_and_b32_e32 v63, 0xffff0000, v64
	v_lshlrev_b32_e32 v64, 16, v65
	v_and_b32_e32 v65, 0xffff0000, v65
	v_pk_fma_f32 v[32:33], v[64:65], 0.5, v[32:33] op_sel_hi:[1,0,1]
	s_waitcnt vmcnt(13)
	v_lshlrev_b32_e32 v64, 16, v73
	v_and_b32_e32 v65, 0xffff0000, v73
	v_pk_fma_f32 v[58:59], v[64:65], 0.5, v[58:59] op_sel_hi:[1,0,1]
	s_waitcnt vmcnt(12)
	v_lshlrev_b32_e32 v64, 16, v75
	v_and_b32_e32 v65, 0xffff0000, v75
	v_pk_fma_f32 v[54:55], v[62:63], 0.5, v[54:55] op_sel_hi:[1,0,1]
	v_lshlrev_b32_e32 v62, 16, v72
	v_and_b32_e32 v63, 0xffff0000, v72
	v_pk_fma_f32 v[30:31], v[64:65], 0.5, v[30:31] op_sel_hi:[1,0,1]
	s_waitcnt vmcnt(11)
	v_lshlrev_b32_e32 v64, 16, v79
	v_and_b32_e32 v65, 0xffff0000, v79
	v_pk_fma_f32 v[60:61], v[62:63], 0.5, v[60:61] op_sel_hi:[1,0,1]
	v_lshlrev_b32_e32 v62, 16, v74
	v_and_b32_e32 v63, 0xffff0000, v74
	v_pk_fma_f32 v[34:35], v[64:65], 0.5, v[34:35] op_sel_hi:[1,0,1]
	s_waitcnt vmcnt(10)
	v_lshlrev_b32_e32 v64, 16, v81
	v_and_b32_e32 v65, 0xffff0000, v81
	v_pk_fma_f32 v[52:53], v[100:101], 0.5, v[52:53] op_sel_hi:[1,0,1]
	v_pk_fma_f32 v[56:57], v[62:63], 0.5, v[56:57] op_sel_hi:[1,0,1]
	v_lshlrev_b32_e32 v62, 16, v78
	v_and_b32_e32 v63, 0xffff0000, v78
	v_pk_fma_f32 v[32:33], v[64:65], 0.5, v[32:33] op_sel_hi:[1,0,1]
	s_waitcnt vmcnt(9)
; template <int MODE>
; DI void norm_phase(const Args& a, const Frame& F, int nslab, float sscale, float* RSTD, const float* SSP) {
;     ...
;                 for (int hb = 0; hb < 2; ++hb) {
;                     u32x2 t[4][4];
; #pragma unroll
;                     for (int s4 = 0; s4 < 4; ++s4) { const int s = hb * 4 + s4; const u32x2* sp = (const u32x2*)((const bf16*)SL + ((size_t)(s < nslab ? s : 0) * NS + (rows[r] - NP)) * DM);
; #pragma unroll
;                         for (int j = 0; j < 4; ++j) t[s4][j] = sp[F.lane + 64 * j]; }
; #pragma unroll
;                     for (int s4 = 0; s4 < 4; ++s4) { const float wsc = (hb * 4 + s4 < nslab) ? sscale : 0.f;
; #pragma unroll
;                         for (int j = 0; j < 4; ++j) v[r][j] = v[r][j] + (f32x4){bflo(t[s4][j].x), bfhi(t[s4][j].x), bflo(t[s4][j].y), bfhi(t[s4][j].y)} * wsc; }
	v_lshlrev_b32_e32 v64, 16, v83
	v_and_b32_e32 v65, 0xffff0000, v83
	v_pk_fma_f32 v[52:53], v[62:63], 0.5, v[52:53] op_sel_hi:[1,0,1]
	v_lshlrev_b32_e32 v62, 16, v80
	v_and_b32_e32 v63, 0xffff0000, v80
	v_pk_fma_f32 v[58:59], v[64:65], 0.5, v[58:59] op_sel_hi:[1,0,1]
	s_waitcnt vmcnt(8)
	v_lshlrev_b32_e32 v64, 16, v77
	v_and_b32_e32 v65, 0xffff0000, v77
	v_pk_fma_f32 v[54:55], v[62:63], 0.5, v[54:55] op_sel_hi:[1,0,1]
	v_lshlrev_b32_e32 v62, 16, v82
	v_and_b32_e32 v63, 0xffff0000, v82
	v_pk_fma_f32 v[30:31], v[64:65], 0.5, v[30:31] op_sel_hi:[1,0,1]
	s_waitcnt vmcnt(7)
	v_lshlrev_b32_e32 v64, 16, v87
	v_and_b32_e32 v65, 0xffff0000, v87
	v_pk_fma_f32 v[60:61], v[62:63], 0.5, v[60:61] op_sel_hi:[1,0,1]
	v_lshlrev_b32_e32 v62, 16, v76
	v_and_b32_e32 v63, 0xffff0000, v76
	v_pk_fma_f32 v[34:35], v[64:65], 0.5, v[34:35] op_sel_hi:[1,0,1]
	s_waitcnt vmcnt(6)
	v_lshlrev_b32_e32 v64, 16, v89
	v_and_b32_e32 v65, 0xffff0000, v89
	v_pk_fma_f32 v[56:57], v[62:63], 0.5, v[56:57] op_sel_hi:[1,0,1]
	v_lshlrev_b32_e32 v62, 16, v86
	v_and_b32_e32 v63, 0xffff0000, v86
	v_pk_fma_f32 v[32:33], v[64:65], 0.5, v[32:33] op_sel_hi:[1,0,1]
	s_waitcnt vmcnt(5)
	v_lshlrev_b32_e32 v64, 16, v91
	v_and_b32_e32 v65, 0xffff0000, v91
	v_pk_fma_f32 v[52:53], v[62:63], 0.5, v[52:53] op_sel_hi:[1,0,1]
	v_lshlrev_b32_e32 v62, 16, v88
	v_and_b32_e32 v63, 0xffff0000, v88
	v_pk_fma_f32 v[64:65], v[64:65], 0.5, v[58:59] op_sel_hi:[1,0,1]
	s_waitcnt vmcnt(4)
	v_lshlrev_b32_e32 v58, 16, v84
	v_and_b32_e32 v59, 0xffff0000, v84
	v_pk_fma_f32 v[54:55], v[62:63], 0.5, v[54:55] op_sel_hi:[1,0,1]
	v_lshlrev_b32_e32 v62, 16, v90
	v_and_b32_e32 v63, 0xffff0000, v90
	v_pk_fma_f32 v[72:73], v[58:59], 0.5, v[56:57] op_sel_hi:[1,0,1]
	s_waitcnt vmcnt(3)
	v_lshlrev_b32_e32 v56, 16, v95
	v_and_b32_e32 v57, 0xffff0000, v95
	v_pk_fma_f32 v[62:63], v[62:63], 0.5, v[60:61] op_sel_hi:[1,0,1]
	v_lshlrev_b32_e32 v60, 16, v85
	v_and_b32_e32 v61, 0xffff0000, v85
	v_lshlrev_b32_e32 v58, 16, v94
	v_and_b32_e32 v59, 0xffff0000, v94
	v_pk_fma_f32 v[56:57], v[56:57], 0.5, v[34:35] op_sel_hi:[1,0,1]
	s_waitcnt vmcnt(2)
	v_lshlrev_b32_e32 v34, 16, v96
	v_and_b32_e32 v35, 0xffff0000, v96
	v_pk_fma_f32 v[30:31], v[60:61], 0.5, v[30:31] op_sel_hi:[1,0,1]
	v_pk_fma_f32 v[60:61], v[58:59], 0.5, v[52:53] op_sel_hi:[1,0,1]
	v_pk_fma_f32 v[58:59], v[34:35], 0.5, v[54:55] op_sel_hi:[1,0,1]
	s_waitcnt vmcnt(1)
	v_lshlrev_b32_e32 v34, 16, v98
	v_and_b32_e32 v35, 0xffff0000, v98
	v_lshlrev_b32_e32 v52, 16, v97
	v_and_b32_e32 v53, 0xffff0000, v97
	v_pk_fma_f32 v[54:55], v[34:35], 0.5, v[62:63] op_sel_hi:[1,0,1]
	s_waitcnt vmcnt(0)
	v_lshlrev_b32_e32 v62, 16, v93
	v_and_b32_e32 v63, 0xffff0000, v93
	v_pk_fma_f32 v[52:53], v[52:53], 0.5, v[32:33] op_sel_hi:[1,0,1]
	v_lshlrev_b32_e32 v32, 16, v99
	v_and_b32_e32 v33, 0xffff0000, v99
	v_pk_fma_f32 v[30:31], v[62:63], 0.5, v[30:31] op_sel_hi:[1,0,1]
	v_lshl_add_u64 v[62:63], v[28:29], 0, s[4:5]
	s_mov_b32 s4, 0x1000000
	v_pk_fma_f32 v[32:33], v[32:33], 0.5, v[64:65] op_sel_hi:[1,0,1]
	v_add_co_u32_e32 v64, vcc, s4, v28
	v_lshlrev_b32_e32 v34, 16, v92
	v_and_b32_e32 v35, 0xffff0000, v92
	v_addc_co_u32_e32 v65, vcc, 0, v29, vcc
	v_pk_fma_f32 v[34:35], v[34:35], 0.5, v[72:73] op_sel_hi:[1,0,1]
	global_load_dwordx2 v[64:65], v[64:65], off
	s_nop 0
	global_load_dwordx2 v[72:73], v[62:63], off offset:512
	global_load_dwordx2 v[74:75], v[62:63], off offset:1024
	s_nop 0
	global_load_dwordx2 v[62:63], v[62:63], off offset:1536
	s_mov_b64 s[4:5], 0x1400000
	v_lshl_add_u64 v[76:77], v[28:29], 0, s[4:5]
	s_mov_b32 s4, 0x1400000
	v_add_co_u32_e32 v78, vcc, s4, v28
	s_mov_b64 s[4:5], 0x1800000
	s_nop 0
	v_addc_co_u32_e32 v79, vcc, 0, v29, vcc
	global_load_dwordx2 v[78:79], v[78:79], off
	s_nop 0
	global_load_dwordx2 v[80:81], v[76:77], off offset:512
	global_load_dwordx2 v[82:83], v[76:77], off offset:1024
	s_nop 0
	global_load_dwordx2 v[76:77], v[76:77], off offset:1536
	v_lshl_add_u64 v[84:85], v[28:29], 0, s[4:5]
	s_mov_b32 s4, 0x1800000
	v_add_co_u32_e32 v86, vcc, s4, v28
	s_mov_b64 s[4:5], 0x1c00000
	s_nop 0
	v_addc_co_u32_e32 v87, vcc, 0, v29, vcc
	global_load_dwordx2 v[86:87], v[86:87], off
	s_nop 0
	global_load_dwordx2 v[88:89], v[84:85], off offset:512
	global_load_dwordx2 v[90:91], v[84:85], off offset:1024
	s_nop 0
	global_load_dwordx2 v[84:85], v[84:85], off offset:1536
	v_lshl_add_u64 v[92:93], v[28:29], 0, s[4:5]
	s_mov_b32 s4, 0x1c00000
	v_add_co_u32_e32 v28, vcc, s4, v28
	s_waitcnt vmcnt(11)
; template <int MODE>
; DI void norm_phase(const Args& a, const Frame& F, int nslab, float sscale, float* RSTD, const float* SSP) {
;     ...
;                 for (int hb = 0; hb < 2; ++hb) {
;                     u32x2 t[4][4];
; #pragma unroll
;                     for (int s4 = 0; s4 < 4; ++s4) { const int s = hb * 4 + s4; const u32x2* sp = (const u32x2*)((const bf16*)SL + ((size_t)(s < nslab ? s : 0) * NS + (rows[r] - NP)) * DM);
; #pragma unroll
;                         for (int j = 0; j < 4; ++j) t[s4][j] = sp[F.lane + 64 * j]; }
; #pragma unroll
;                     for (int s4 = 0; s4 < 4; ++s4) { const float wsc = (hb * 4 + s4 < nslab) ? sscale : 0.f;
; #pragma unroll
;                         for (int j = 0; j < 4; ++j) v[r][j] = v[r][j] + (f32x4){bflo(t[s4][j].x), bfhi(t[s4][j].x), bflo(t[s4][j].y), bfhi(t[s4][j].y)} * wsc; }
	v_lshlrev_b32_e32 v98, 16, v64
	v_addc_co_u32_e32 v29, vcc, 0, v29, vcc
	global_load_dwordx2 v[28:29], v[28:29], off
	s_nop 0
	global_load_dwordx2 v[94:95], v[92:93], off offset:512
	global_load_dwordx2 v[96:97], v[92:93], off offset:1024
	s_nop 0
	global_load_dwordx2 v[92:93], v[92:93], off offset:1536
	v_and_b32_e32 v99, 0xffff0000, v64
	v_lshlrev_b32_e32 v64, 16, v65
	v_and_b32_e32 v65, 0xffff0000, v65
	v_pk_fma_f32 v[56:57], v[64:65], 0.5, v[56:57] op_sel_hi:[1,0,1]
	s_waitcnt vmcnt(14)
	v_lshlrev_b32_e32 v64, 16, v72
	v_and_b32_e32 v65, 0xffff0000, v72
	v_pk_fma_f32 v[58:59], v[64:65], 0.5, v[58:59] op_sel_hi:[1,0,1]
	s_waitcnt vmcnt(13)
	v_lshlrev_b32_e32 v64, 16, v74
	v_and_b32_e32 v65, 0xffff0000, v74
	v_pk_fma_f32 v[54:55], v[64:65], 0.5, v[54:55] op_sel_hi:[1,0,1]
	s_waitcnt vmcnt(12)
	v_lshlrev_b32_e32 v64, 16, v62
	v_and_b32_e32 v65, 0xffff0000, v62
	v_lshlrev_b32_e32 v62, 16, v63
	v_and_b32_e32 v63, 0xffff0000, v63
	v_pk_fma_f32 v[60:61], v[98:99], 0.5, v[60:61] op_sel_hi:[1,0,1]
	v_lshlrev_b32_e32 v72, 16, v73
	v_and_b32_e32 v73, 0xffff0000, v73
	v_pk_fma_f32 v[34:35], v[64:65], 0.5, v[34:35] op_sel_hi:[1,0,1]
	v_pk_fma_f32 v[30:31], v[62:63], 0.5, v[30:31] op_sel_hi:[1,0,1]
	s_waitcnt vmcnt(11)
	v_lshlrev_b32_e32 v62, 16, v78
	v_and_b32_e32 v63, 0xffff0000, v78
	v_lshlrev_b32_e32 v64, 16, v79
	v_and_b32_e32 v65, 0xffff0000, v79
	v_pk_fma_f32 v[52:53], v[72:73], 0.5, v[52:53] op_sel_hi:[1,0,1]
	v_lshlrev_b32_e32 v72, 16, v75
	v_and_b32_e32 v73, 0xffff0000, v75
	v_pk_fma_f32 v[56:57], v[64:65], 0.5, v[56:57] op_sel_hi:[1,0,1]
	v_pk_fma_f32 v[60:61], v[62:63], 0.5, v[60:61] op_sel_hi:[1,0,1]
	s_waitcnt vmcnt(10)
	v_lshlrev_b32_e32 v62, 16, v80
	v_and_b32_e32 v63, 0xffff0000, v80
	v_lshlrev_b32_e32 v64, 16, v81
	v_and_b32_e32 v65, 0xffff0000, v81
	v_pk_fma_f32 v[32:33], v[72:73], 0.5, v[32:33] op_sel_hi:[1,0,1]
	v_pk_fma_f32 v[52:53], v[64:65], 0.5, v[52:53] op_sel_hi:[1,0,1]
	v_pk_fma_f32 v[58:59], v[62:63], 0.5, v[58:59] op_sel_hi:[1,0,1]
	s_waitcnt vmcnt(9)
	v_lshlrev_b32_e32 v62, 16, v82
	v_and_b32_e32 v63, 0xffff0000, v82
	v_lshlrev_b32_e32 v64, 16, v83
	v_and_b32_e32 v65, 0xffff0000, v83
	v_pk_fma_f32 v[32:33], v[64:65], 0.5, v[32:33] op_sel_hi:[1,0,1]
	v_pk_fma_f32 v[54:55], v[62:63], 0.5, v[54:55] op_sel_hi:[1,0,1]
	s_waitcnt vmcnt(8)
	v_lshlrev_b32_e32 v62, 16, v76
	v_and_b32_e32 v63, 0xffff0000, v76
	v_lshlrev_b32_e32 v64, 16, v77
	v_and_b32_e32 v65, 0xffff0000, v77
	v_pk_fma_f32 v[30:31], v[64:65], 0.5, v[30:31] op_sel_hi:[1,0,1]
	v_pk_fma_f32 v[34:35], v[62:63], 0.5, v[34:35] op_sel_hi:[1,0,1]
	s_waitcnt vmcnt(7)
	v_lshlrev_b32_e32 v62, 16, v86
	v_and_b32_e32 v63, 0xffff0000, v86
	v_lshlrev_b32_e32 v64, 16, v87
	v_and_b32_e32 v65, 0xffff0000, v87
	v_pk_fma_f32 v[60:61], v[62:63], 0.5, v[60:61] op_sel_hi:[1,0,1]
	v_pk_fma_f32 v[56:57], v[64:65], 0.5, v[56:57] op_sel_hi:[1,0,1]
	s_waitcnt vmcnt(6)
	v_lshlrev_b32_e32 v62, 16, v88
	v_and_b32_e32 v63, 0xffff0000, v88
	v_lshlrev_b32_e32 v64, 16, v89
	v_and_b32_e32 v65, 0xffff0000, v89
	v_pk_fma_f32 v[58:59], v[62:63], 0.5, v[58:59] op_sel_hi:[1,0,1]
	v_pk_fma_f32 v[62:63], v[64:65], 0.5, v[52:53] op_sel_hi:[1,0,1]
	s_waitcnt vmcnt(5)
	v_lshlrev_b32_e32 v64, 16, v91
	v_and_b32_e32 v65, 0xffff0000, v91
	v_pk_fma_f32 v[64:65], v[64:65], 0.5, v[32:33] op_sel_hi:[1,0,1]
	s_waitcnt vmcnt(4)
	v_lshlrev_b32_e32 v32, 16, v84
	v_and_b32_e32 v33, 0xffff0000, v84
	v_pk_fma_f32 v[74:75], v[32:33], 0.5, v[34:35] op_sel_hi:[1,0,1]
	v_lshlrev_b32_e32 v52, 16, v90
	v_and_b32_e32 v53, 0xffff0000, v90
	v_pk_fma_f32 v[72:73], v[52:53], 0.5, v[54:55] op_sel_hi:[1,0,1]
	v_lshlrev_b32_e32 v52, 16, v85
	v_and_b32_e32 v53, 0xffff0000, v85
	v_pk_fma_f32 v[30:31], v[52:53], 0.5, v[30:31] op_sel_hi:[1,0,1]
	s_waitcnt vmcnt(3)
	v_lshlrev_b32_e32 v32, 16, v28
	v_and_b32_e32 v33, 0xffff0000, v28
	v_lshlrev_b32_e32 v28, 16, v29
	v_and_b32_e32 v29, 0xffff0000, v29
	v_pk_fma_f32 v[34:35], v[28:29], 0.5, v[56:57] op_sel_hi:[1,0,1]
	s_waitcnt vmcnt(2)
	v_lshlrev_b32_e32 v28, 16, v94
	v_and_b32_e32 v29, 0xffff0000, v94
	v_pk_fma_f32 v[54:55], v[28:29], 0.5, v[58:59] op_sel_hi:[1,0,1]
	s_waitcnt vmcnt(1)
	v_lshlrev_b32_e32 v28, 16, v96
	v_and_b32_e32 v29, 0xffff0000, v96
	v_lshlrev_b32_e32 v56, 16, v97
	v_and_b32_e32 v57, 0xffff0000, v97
	v_pk_fma_f32 v[52:53], v[32:33], 0.5, v[60:61] op_sel_hi:[1,0,1]
	v_lshlrev_b32_e32 v32, 16, v95
	v_and_b32_e32 v33, 0xffff0000, v95
	v_pk_fma_f32 v[58:59], v[56:57], 0.5, v[64:65] op_sel_hi:[1,0,1]
	v_pk_fma_f32 v[60:61], v[28:29], 0.5, v[72:73] op_sel_hi:[1,0,1]
	s_waitcnt vmcnt(0)
	v_lshlrev_b32_e32 v28, 16, v92
	v_and_b32_e32 v29, 0xffff0000, v92
	v_lshlrev_b32_e32 v56, 16, v93
	v_and_b32_e32 v57, 0xffff0000, v93
	v_pk_fma_f32 v[32:33], v[32:33], 0.5, v[62:63] op_sel_hi:[1,0,1]
	v_pk_fma_f32 v[30:31], v[56:57], 0.5, v[30:31] op_sel_hi:[1,0,1]
	v_pk_fma_f32 v[56:57], v[28:29], 0.5, v[74:75] op_sel_hi:[1,0,1]

; template <int MODE>
; DI void norm_phase(const Args& a, const Frame& F, int nslab, float sscale, float* RSTD, const float* SSP) {
;     ...
;         if (MODE != 1 && nslab > 0) {
; #pragma unroll
;             for (int r = 0; r < RB; ++r) if (rows[r] >= NP) {
; #pragma unroll
;                 for (int hb = 0; hb < 2; ++hb) {
;                     u32x2 t[4][4];
; #pragma unroll
;                     for (int s4 = 0; s4 < 4; ++s4) { const int s = hb * 4 + s4; const u32x2* sp = (const u32x2*)((const bf16*)SL + ((size_t)(s < nslab ? s : 0) * NS + (rows[r] - NP)) * DM);
; #pragma unroll
;                         for (int j = 0; j < 4; ++j) t[s4][j] = sp[F.lane + 64 * j]; }
; #pragma unroll
;                     for (int s4 = 0; s4 < 4; ++s4) { const float wsc = (hb * 4 + s4 < nslab) ? sscale : 0.f;
; #pragma unroll
;                         for (int j = 0; j < 4; ++j) v[r][j] = v[r][j] + (f32x4){bflo(t[s4][j].x), bfhi(t[s4][j].x), bflo(t[s4][j].y), bfhi(t[s4][j].y)} * wsc; }
.LBB0_1857:
	s_waitcnt vmcnt(7)
	v_lshlrev_b32_e32 v50, 16, v42
	v_and_b32_e32 v51, 0xffff0000, v42
	v_lshlrev_b32_e32 v48, 16, v43
	v_and_b32_e32 v49, 0xffff0000, v43
	s_waitcnt vmcnt(6)
	v_lshlrev_b32_e32 v46, 16, v40
	v_and_b32_e32 v47, 0xffff0000, v40
	v_lshlrev_b32_e32 v44, 16, v41
	v_and_b32_e32 v45, 0xffff0000, v41
	s_waitcnt vmcnt(5)
	v_lshlrev_b32_e32 v42, 16, v38
	v_and_b32_e32 v43, 0xffff0000, v38
	v_lshlrev_b32_e32 v40, 16, v39
	v_and_b32_e32 v41, 0xffff0000, v39
	s_waitcnt vmcnt(4)
	v_lshlrev_b32_e32 v38, 16, v36
	v_and_b32_e32 v39, 0xffff0000, v36
	v_lshlrev_b32_e32 v36, 16, v37
	s_cmpk_lt_i32 s12, 0x4000
	v_and_b32_e32 v37, 0xffff0000, v37
	s_cbranch_scc1 .LBB0_1859
	s_cmp_eq_u64 s[14:15], 0
	s_cbranch_scc1 .LBB0_1859
	s_add_i32 s62, s12, 0xffffc000
	s_lshl_b64 s[4:5], s[62:63], 11
	s_add_u32 s4, s77, s4
	s_addc_u32 s5, s66, s5
	v_lshl_add_u64 v[52:53], v[160:161], 3, s[4:5]
	v_add_co_u32_e32 v60, vcc, s33, v52
	global_load_dwordx2 v[54:55], v[52:53], off
	global_load_dwordx2 v[58:59], v[52:53], off offset:512
	s_waitcnt lgkmcnt(2)
	global_load_dwordx2 v[64:65], v[52:53], off offset:1024
	global_load_dwordx2 v[70:71], v[52:53], off offset:1536
	s_waitcnt lgkmcnt(0)
	v_addc_co_u32_e32 v61, vcc, 0, v53, vcc
	v_lshl_add_u64 v[56:57], v[52:53], 0, s[82:83]
	global_load_dwordx2 v[78:79], v[60:61], off
	global_load_dwordx2 v[80:81], v[56:57], off offset:512
	global_load_dwordx2 v[82:83], v[56:57], off offset:1024
	global_load_dwordx2 v[84:85], v[56:57], off offset:1536
	s_mov_b64 s[4:5], 0x800000
	v_lshl_add_u64 v[56:57], v[52:53], 0, s[4:5]
	s_mov_b32 s4, 0x800000
	v_add_co_u32_e32 v60, vcc, s4, v52
	s_mov_b64 s[4:5], 0xc00000
	s_nop 0
	v_addc_co_u32_e32 v61, vcc, 0, v53, vcc
	global_load_dwordx2 v[92:93], v[60:61], off
	global_load_dwordx2 v[94:95], v[56:57], off offset:512
	global_load_dwordx2 v[96:97], v[56:57], off offset:1024
	global_load_dwordx2 v[74:75], v[56:57], off offset:1536
	v_lshl_add_u64 v[56:57], v[52:53], 0, s[4:5]
	s_mov_b32 s4, 0xc00000
	v_add_co_u32_e32 v52, vcc, s4, v52
	s_waitcnt vmcnt(9)
	v_lshlrev_b32_e32 v60, 16, v64
	v_addc_co_u32_e32 v53, vcc, 0, v53, vcc
	global_load_dwordx2 v[76:77], v[52:53], off
	global_load_dwordx2 v[72:73], v[56:57], off offset:512
	global_load_dwordx2 v[66:67], v[56:57], off offset:1024
	global_load_dwordx2 v[62:63], v[56:57], off offset:1536
	v_lshlrev_b32_e32 v52, 16, v54
	v_and_b32_e32 v53, 0xffff0000, v54
	v_lshlrev_b32_e32 v54, 16, v55
	v_and_b32_e32 v55, 0xffff0000, v55
	v_pk_add_f32 v[48:49], v[48:49], v[54:55]
	v_lshlrev_b32_e32 v56, 16, v58
	v_and_b32_e32 v57, 0xffff0000, v58
	s_waitcnt vmcnt(11)
	v_lshlrev_b32_e32 v98, 16, v78
	v_and_b32_e32 v99, 0xffff0000, v78
	v_lshlrev_b32_e32 v78, 16, v79
	v_and_b32_e32 v79, 0xffff0000, v79
	v_pk_add_f32 v[46:47], v[46:47], v[56:57]
	v_and_b32_e32 v61, 0xffff0000, v64
	v_pk_add_f32 v[48:49], v[48:49], v[78:79]
	s_waitcnt vmcnt(10)
	v_lshlrev_b32_e32 v78, 16, v80
	v_and_b32_e32 v79, 0xffff0000, v80
	v_pk_add_f32 v[42:43], v[42:43], v[60:61]
	v_lshlrev_b32_e32 v68, 16, v70
	v_and_b32_e32 v69, 0xffff0000, v70
	v_pk_add_f32 v[46:47], v[46:47], v[78:79]
	s_waitcnt vmcnt(9)
	v_lshlrev_b32_e32 v78, 16, v82
	v_and_b32_e32 v79, 0xffff0000, v82
	v_pk_add_f32 v[50:51], v[50:51], v[52:53]
	v_lshlrev_b32_e32 v58, 16, v59
	v_and_b32_e32 v59, 0xffff0000, v59
	v_pk_add_f32 v[38:39], v[38:39], v[68:69]
	v_pk_add_f32 v[42:43], v[42:43], v[78:79]
	s_waitcnt vmcnt(8)
	v_lshlrev_b32_e32 v78, 16, v84
	v_and_b32_e32 v79, 0xffff0000, v84
	v_pk_add_f32 v[44:45], v[44:45], v[58:59]
	v_lshlrev_b32_e32 v64, 16, v65
	v_and_b32_e32 v65, 0xffff0000, v65
	v_pk_add_f32 v[50:51], v[50:51], v[98:99]
	v_lshlrev_b32_e32 v80, 16, v81
	v_and_b32_e32 v81, 0xffff0000, v81
	v_pk_add_f32 v[38:39], v[38:39], v[78:79]
	s_waitcnt vmcnt(7)
	v_lshlrev_b32_e32 v78, 16, v92
	v_and_b32_e32 v79, 0xffff0000, v92
	v_pk_add_f32 v[40:41], v[40:41], v[64:65]
	v_lshlrev_b32_e32 v70, 16, v71
	v_and_b32_e32 v71, 0xffff0000, v71
	v_pk_add_f32 v[44:45], v[44:45], v[80:81]
	v_lshlrev_b32_e32 v80, 16, v83
	v_and_b32_e32 v81, 0xffff0000, v83
	v_pk_add_f32 v[50:51], v[50:51], v[78:79]
	s_waitcnt vmcnt(6)
	v_lshlrev_b32_e32 v78, 16, v94
	v_and_b32_e32 v79, 0xffff0000, v94
	v_pk_add_f32 v[36:37], v[36:37], v[70:71]
	v_pk_add_f32 v[40:41], v[40:41], v[80:81]
	v_lshlrev_b32_e32 v80, 16, v85
	v_and_b32_e32 v81, 0xffff0000, v85
	v_pk_add_f32 v[46:47], v[46:47], v[78:79]
	s_waitcnt vmcnt(5)
	v_lshlrev_b32_e32 v78, 16, v96
	v_and_b32_e32 v79, 0xffff0000, v96
	v_pk_add_f32 v[36:37], v[36:37], v[80:81]
	v_lshlrev_b32_e32 v80, 16, v93
	v_and_b32_e32 v81, 0xffff0000, v93
	v_pk_add_f32 v[42:43], v[42:43], v[78:79]
	s_waitcnt vmcnt(4)
	v_lshlrev_b32_e32 v78, 16, v74
	v_and_b32_e32 v79, 0xffff0000, v74
	v_lshlrev_b32_e32 v74, 16, v75
	v_and_b32_e32 v75, 0xffff0000, v75
	v_pk_add_f32 v[48:49], v[48:49], v[80:81]
	v_lshlrev_b32_e32 v80, 16, v95
	v_and_b32_e32 v81, 0xffff0000, v95
	v_pk_add_f32 v[36:37], v[36:37], v[74:75]
	v_pk_add_f32 v[44:45], v[44:45], v[80:81]
	v_lshlrev_b32_e32 v80, 16, v97
	v_and_b32_e32 v81, 0xffff0000, v97
	v_pk_add_f32 v[40:41], v[40:41], v[80:81]
	v_pk_add_f32 v[38:39], v[38:39], v[78:79]
	s_waitcnt vmcnt(3)
	v_lshlrev_b32_e32 v74, 16, v76
	v_and_b32_e32 v75, 0xffff0000, v76
	v_pk_add_f32 v[50:51], v[50:51], v[74:75]
	s_waitcnt vmcnt(2)
	v_lshlrev_b32_e32 v74, 16, v72
	v_and_b32_e32 v75, 0xffff0000, v72
	v_lshlrev_b32_e32 v72, 16, v73
	v_and_b32_e32 v73, 0xffff0000, v73
	v_pk_add_f32 v[44:45], v[44:45], v[72:73]
	s_waitcnt vmcnt(1)
	v_lshlrev_b32_e32 v72, 16, v66
	v_and_b32_e32 v73, 0xffff0000, v66
	v_lshlrev_b32_e32 v66, 16, v67
	v_and_b32_e32 v67, 0xffff0000, v67
	v_lshlrev_b32_e32 v76, 16, v77
	v_and_b32_e32 v77, 0xffff0000, v77
	v_pk_add_f32 v[40:41], v[40:41], v[66:67]
	s_waitcnt vmcnt(0)
; template <int MODE>
; DI void norm_phase(const Args& a, const Frame& F, int nslab, float sscale, float* RSTD, const float* SSP) {
;     ...
;                 for (int hb = 0; hb < 2; ++hb) {
;                     u32x2 t[4][4];
; #pragma unroll
;                     for (int s4 = 0; s4 < 4; ++s4) { const int s = hb * 4 + s4; const u32x2* sp = (const u32x2*)((const bf16*)SL + ((size_t)(s < nslab ? s : 0) * NS + (rows[r] - NP)) * DM);
; #pragma unroll
;                         for (int j = 0; j < 4; ++j) t[s4][j] = sp[F.lane + 64 * j]; }
; #pragma unroll
;                     for (int s4 = 0; s4 < 4; ++s4) { const float wsc = (hb * 4 + s4 < nslab) ? sscale : 0.f;
; #pragma unroll
;                         for (int j = 0; j < 4; ++j) v[r][j] = v[r][j] + (f32x4){bflo(t[s4][j].x), bfhi(t[s4][j].x), bflo(t[s4][j].y), bfhi(t[s4][j].y)} * wsc; }
	v_lshlrev_b32_e32 v66, 16, v62
	v_and_b32_e32 v67, 0xffff0000, v62
	v_lshlrev_b32_e32 v62, 16, v63
	v_and_b32_e32 v63, 0xffff0000, v63
	v_pk_add_f32 v[48:49], v[48:49], v[76:77]
	v_pk_add_f32 v[46:47], v[46:47], v[74:75]
	v_pk_add_f32 v[42:43], v[42:43], v[72:73]
	v_pk_add_f32 v[36:37], v[36:37], v[62:63]
	v_pk_add_f32 v[38:39], v[38:39], v[66:67]
	v_pk_fma_f32 v[50:51], v[52:53], 0, v[50:51] op_sel_hi:[1,0,1]
	v_pk_fma_f32 v[48:49], v[54:55], 0, v[48:49] op_sel_hi:[1,0,1]
	v_pk_fma_f32 v[46:47], v[56:57], 0, v[46:47] op_sel_hi:[1,0,1]
	v_pk_fma_f32 v[44:45], v[58:59], 0, v[44:45] op_sel_hi:[1,0,1]
	v_pk_fma_f32 v[42:43], v[60:61], 0, v[42:43] op_sel_hi:[1,0,1]
	v_pk_fma_f32 v[40:41], v[64:65], 0, v[40:41] op_sel_hi:[1,0,1]
	v_pk_fma_f32 v[38:39], v[68:69], 0, v[38:39] op_sel_hi:[1,0,1]
	v_pk_fma_f32 v[36:37], v[70:71], 0, v[36:37] op_sel_hi:[1,0,1]
	v_pk_fma_f32 v[48:49], v[54:55], 0, v[48:49] op_sel_hi:[1,0,1]
	v_pk_fma_f32 v[50:51], v[52:53], 0, v[50:51] op_sel_hi:[1,0,1]
	v_pk_fma_f32 v[44:45], v[58:59], 0, v[44:45] op_sel_hi:[1,0,1]
	v_pk_fma_f32 v[46:47], v[56:57], 0, v[46:47] op_sel_hi:[1,0,1]
	v_pk_fma_f32 v[40:41], v[64:65], 0, v[40:41] op_sel_hi:[1,0,1]
	v_pk_fma_f32 v[42:43], v[60:61], 0, v[42:43] op_sel_hi:[1,0,1]
	v_pk_fma_f32 v[36:37], v[70:71], 0, v[36:37] op_sel_hi:[1,0,1]
	v_pk_fma_f32 v[38:39], v[68:69], 0, v[38:39] op_sel_hi:[1,0,1]
	v_pk_fma_f32 v[50:51], v[52:53], 0, v[50:51] op_sel_hi:[1,0,1]
	v_pk_fma_f32 v[48:49], v[54:55], 0, v[48:49] op_sel_hi:[1,0,1]
	v_pk_fma_f32 v[46:47], v[56:57], 0, v[46:47] op_sel_hi:[1,0,1]
	v_pk_fma_f32 v[44:45], v[58:59], 0, v[44:45] op_sel_hi:[1,0,1]
	v_pk_fma_f32 v[42:43], v[60:61], 0, v[42:43] op_sel_hi:[1,0,1]
	v_pk_fma_f32 v[40:41], v[64:65], 0, v[40:41] op_sel_hi:[1,0,1]
	v_pk_fma_f32 v[38:39], v[68:69], 0, v[38:39] op_sel_hi:[1,0,1]
	v_pk_fma_f32 v[36:37], v[70:71], 0, v[36:37] op_sel_hi:[1,0,1]
	v_pk_fma_f32 v[48:49], v[54:55], 0, v[48:49] op_sel_hi:[1,0,1]
	v_pk_fma_f32 v[50:51], v[52:53], 0, v[50:51] op_sel_hi:[1,0,1]
	v_pk_fma_f32 v[44:45], v[58:59], 0, v[44:45] op_sel_hi:[1,0,1]
	v_pk_fma_f32 v[46:47], v[56:57], 0, v[46:47] op_sel_hi:[1,0,1]
	v_pk_fma_f32 v[40:41], v[64:65], 0, v[40:41] op_sel_hi:[1,0,1]
	v_pk_fma_f32 v[42:43], v[60:61], 0, v[42:43] op_sel_hi:[1,0,1]
	v_pk_fma_f32 v[36:37], v[70:71], 0, v[36:37] op_sel_hi:[1,0,1]
	v_pk_fma_f32 v[38:39], v[68:69], 0, v[38:39] op_sel_hi:[1,0,1]
.LBB0_1859:
	s_waitcnt vmcnt(3)
	v_lshlrev_b32_e32 v58, 16, v34
	v_and_b32_e32 v59, 0xffff0000, v34
	v_lshlrev_b32_e32 v56, 16, v35
	v_and_b32_e32 v57, 0xffff0000, v35
	s_waitcnt vmcnt(2)
	v_lshlrev_b32_e32 v54, 16, v32
	v_and_b32_e32 v55, 0xffff0000, v32
	v_lshlrev_b32_e32 v52, 16, v33
	v_and_b32_e32 v53, 0xffff0000, v33
	s_waitcnt vmcnt(1)
	v_lshlrev_b32_e32 v34, 16, v30
	v_and_b32_e32 v35, 0xffff0000, v30
	v_lshlrev_b32_e32 v32, 16, v31
	v_and_b32_e32 v33, 0xffff0000, v31
	s_waitcnt vmcnt(0)
	v_lshlrev_b32_e32 v30, 16, v28
	v_and_b32_e32 v31, 0xffff0000, v28
	v_lshlrev_b32_e32 v28, 16, v29
	s_cmpk_lt_i32 s8, 0x4000
	v_and_b32_e32 v29, 0xffff0000, v29
	s_cbranch_scc1 .LBB0_1861
	s_cmp_eq_u64 s[10:11], 0
	s_cbranch_scc1 .LBB0_1861
	s_add_i32 s62, s8, 0xffffc000
	s_lshl_b64 s[4:5], s[62:63], 11
	s_add_u32 s4, s77, s4
	s_addc_u32 s5, s66, s5
	s_waitcnt lgkmcnt(0)
	v_lshl_add_u64 v[60:61], v[160:161], 3, s[4:5]
	v_add_co_u32_e32 v68, vcc, s33, v60
	global_load_dwordx2 v[62:63], v[60:61], off
	global_load_dwordx2 v[66:67], v[60:61], off offset:512
	global_load_dwordx2 v[72:73], v[60:61], off offset:1024
	global_load_dwordx2 v[78:79], v[60:61], off offset:1536
	v_addc_co_u32_e32 v69, vcc, 0, v61, vcc
	v_lshl_add_u64 v[64:65], v[60:61], 0, s[82:83]
	global_load_dwordx2 v[92:93], v[68:69], off
	global_load_dwordx2 v[94:95], v[64:65], off offset:512
	global_load_dwordx2 v[96:97], v[64:65], off offset:1024
	global_load_dwordx2 v[98:99], v[64:65], off offset:1536
	s_mov_b64 s[4:5], 0x800000
	v_lshl_add_u64 v[64:65], v[60:61], 0, s[4:5]
	s_mov_b32 s4, 0x800000
	v_add_co_u32_e32 v68, vcc, s4, v60
	s_mov_b64 s[4:5], 0xc00000
	s_nop 0
	v_addc_co_u32_e32 v69, vcc, 0, v61, vcc
	global_load_dwordx2 v[100:101], v[68:69], off
	global_load_dwordx2 v[102:103], v[64:65], off offset:512
	global_load_dwordx2 v[104:105], v[64:65], off offset:1024
	global_load_dwordx2 v[82:83], v[64:65], off offset:1536
	v_lshl_add_u64 v[64:65], v[60:61], 0, s[4:5]
	s_mov_b32 s4, 0xc00000
	v_add_co_u32_e32 v60, vcc, s4, v60
	s_waitcnt vmcnt(9)
	v_lshlrev_b32_e32 v68, 16, v72
	v_addc_co_u32_e32 v61, vcc, 0, v61, vcc
	global_load_dwordx2 v[84:85], v[60:61], off
	global_load_dwordx2 v[80:81], v[64:65], off offset:512
	global_load_dwordx2 v[74:75], v[64:65], off offset:1024
	global_load_dwordx2 v[70:71], v[64:65], off offset:1536
	v_lshlrev_b32_e32 v60, 16, v62
	v_and_b32_e32 v61, 0xffff0000, v62
	v_lshlrev_b32_e32 v62, 16, v63
	v_and_b32_e32 v63, 0xffff0000, v63
	v_pk_add_f32 v[56:57], v[56:57], v[62:63]
	v_lshlrev_b32_e32 v64, 16, v66
	v_and_b32_e32 v65, 0xffff0000, v66
	s_waitcnt vmcnt(11)
	v_lshlrev_b32_e32 v106, 16, v92
	v_and_b32_e32 v107, 0xffff0000, v92
	v_lshlrev_b32_e32 v92, 16, v93
	v_and_b32_e32 v93, 0xffff0000, v93
	v_pk_add_f32 v[54:55], v[54:55], v[64:65]
	v_and_b32_e32 v69, 0xffff0000, v72
	v_pk_add_f32 v[56:57], v[56:57], v[92:93]
	s_waitcnt vmcnt(10)
; template <int MODE>
; DI void norm_phase(const Args& a, const Frame& F, int nslab, float sscale, float* RSTD, const float* SSP) {
;     ...
;                 for (int hb = 0; hb < 2; ++hb) {
;                     u32x2 t[4][4];
; #pragma unroll
;                     for (int s4 = 0; s4 < 4; ++s4) { const int s = hb * 4 + s4; const u32x2* sp = (const u32x2*)((const bf16*)SL + ((size_t)(s < nslab ? s : 0) * NS + (rows[r] - NP)) * DM);
; #pragma unroll
;                         for (int j = 0; j < 4; ++j) t[s4][j] = sp[F.lane + 64 * j]; }
; #pragma unroll
;                     for (int s4 = 0; s4 < 4; ++s4) { const float wsc = (hb * 4 + s4 < nslab) ? sscale : 0.f;
; #pragma unroll
;                         for (int j = 0; j < 4; ++j) v[r][j] = v[r][j] + (f32x4){bflo(t[s4][j].x), bfhi(t[s4][j].x), bflo(t[s4][j].y), bfhi(t[s4][j].y)} * wsc; }
	v_lshlrev_b32_e32 v92, 16, v94
	v_and_b32_e32 v93, 0xffff0000, v94
	v_pk_add_f32 v[34:35], v[34:35], v[68:69]
	v_lshlrev_b32_e32 v76, 16, v78
	v_and_b32_e32 v77, 0xffff0000, v78
	v_pk_add_f32 v[54:55], v[54:55], v[92:93]
	s_waitcnt vmcnt(9)
	v_lshlrev_b32_e32 v92, 16, v96
	v_and_b32_e32 v93, 0xffff0000, v96
	v_pk_add_f32 v[58:59], v[58:59], v[60:61]
	v_lshlrev_b32_e32 v66, 16, v67
	v_and_b32_e32 v67, 0xffff0000, v67
	v_pk_add_f32 v[30:31], v[30:31], v[76:77]
	v_pk_add_f32 v[34:35], v[34:35], v[92:93]
	s_waitcnt vmcnt(8)
	v_lshlrev_b32_e32 v92, 16, v98
	v_and_b32_e32 v93, 0xffff0000, v98
	v_pk_add_f32 v[52:53], v[52:53], v[66:67]
	v_lshlrev_b32_e32 v72, 16, v73
	v_and_b32_e32 v73, 0xffff0000, v73
	v_pk_add_f32 v[58:59], v[58:59], v[106:107]
	v_lshlrev_b32_e32 v94, 16, v95
	v_and_b32_e32 v95, 0xffff0000, v95
	v_pk_add_f32 v[30:31], v[30:31], v[92:93]
	s_waitcnt vmcnt(7)
	v_lshlrev_b32_e32 v92, 16, v100
	v_and_b32_e32 v93, 0xffff0000, v100
	v_pk_add_f32 v[32:33], v[32:33], v[72:73]
	v_lshlrev_b32_e32 v78, 16, v79
	v_and_b32_e32 v79, 0xffff0000, v79
	v_pk_add_f32 v[52:53], v[52:53], v[94:95]
	v_lshlrev_b32_e32 v94, 16, v97
	v_and_b32_e32 v95, 0xffff0000, v97
	v_pk_add_f32 v[58:59], v[58:59], v[92:93]
	s_waitcnt vmcnt(6)
	v_lshlrev_b32_e32 v92, 16, v102
	v_and_b32_e32 v93, 0xffff0000, v102
	v_pk_add_f32 v[28:29], v[28:29], v[78:79]
	v_pk_add_f32 v[32:33], v[32:33], v[94:95]
	v_lshlrev_b32_e32 v94, 16, v99
	v_and_b32_e32 v95, 0xffff0000, v99
	v_pk_add_f32 v[54:55], v[54:55], v[92:93]
	s_waitcnt vmcnt(5)
	v_lshlrev_b32_e32 v92, 16, v104
	v_and_b32_e32 v93, 0xffff0000, v104
	v_pk_add_f32 v[28:29], v[28:29], v[94:95]
	v_lshlrev_b32_e32 v94, 16, v101
	v_and_b32_e32 v95, 0xffff0000, v101
	v_pk_add_f32 v[34:35], v[34:35], v[92:93]
	s_waitcnt vmcnt(4)
	v_lshlrev_b32_e32 v92, 16, v82
	v_and_b32_e32 v93, 0xffff0000, v82
	v_lshlrev_b32_e32 v82, 16, v83
	v_and_b32_e32 v83, 0xffff0000, v83
	v_pk_add_f32 v[56:57], v[56:57], v[94:95]
	v_lshlrev_b32_e32 v94, 16, v103
	v_and_b32_e32 v95, 0xffff0000, v103
	v_pk_add_f32 v[28:29], v[28:29], v[82:83]
	v_pk_add_f32 v[52:53], v[52:53], v[94:95]
	v_lshlrev_b32_e32 v94, 16, v105
	v_and_b32_e32 v95, 0xffff0000, v105
	v_pk_add_f32 v[32:33], v[32:33], v[94:95]
	v_pk_add_f32 v[30:31], v[30:31], v[92:93]
	s_waitcnt vmcnt(3)
	v_lshlrev_b32_e32 v82, 16, v84
	v_and_b32_e32 v83, 0xffff0000, v84
	v_pk_add_f32 v[58:59], v[58:59], v[82:83]
	s_waitcnt vmcnt(2)
	v_lshlrev_b32_e32 v82, 16, v80
	v_and_b32_e32 v83, 0xffff0000, v80
	v_lshlrev_b32_e32 v80, 16, v81
	v_and_b32_e32 v81, 0xffff0000, v81
	v_pk_add_f32 v[52:53], v[52:53], v[80:81]
	s_waitcnt vmcnt(1)
	v_lshlrev_b32_e32 v80, 16, v74
	v_and_b32_e32 v81, 0xffff0000, v74
	v_lshlrev_b32_e32 v74, 16, v75
	v_and_b32_e32 v75, 0xffff0000, v75
	v_lshlrev_b32_e32 v84, 16, v85
	v_and_b32_e32 v85, 0xffff0000, v85
	v_pk_add_f32 v[32:33], v[32:33], v[74:75]
	s_waitcnt vmcnt(0)
	v_lshlrev_b32_e32 v74, 16, v70
	v_and_b32_e32 v75, 0xffff0000, v70
	v_lshlrev_b32_e32 v70, 16, v71
	v_and_b32_e32 v71, 0xffff0000, v71
	v_pk_add_f32 v[56:57], v[56:57], v[84:85]
	v_pk_add_f32 v[54:55], v[54:55], v[82:83]
	v_pk_add_f32 v[34:35], v[34:35], v[80:81]
	v_pk_add_f32 v[28:29], v[28:29], v[70:71]
	v_pk_add_f32 v[30:31], v[30:31], v[74:75]
	v_pk_fma_f32 v[58:59], v[60:61], 0, v[58:59] op_sel_hi:[1,0,1]
	v_pk_fma_f32 v[56:57], v[62:63], 0, v[56:57] op_sel_hi:[1,0,1]
	v_pk_fma_f32 v[54:55], v[64:65], 0, v[54:55] op_sel_hi:[1,0,1]
	v_pk_fma_f32 v[52:53], v[66:67], 0, v[52:53] op_sel_hi:[1,0,1]
	v_pk_fma_f32 v[34:35], v[68:69], 0, v[34:35] op_sel_hi:[1,0,1]
	v_pk_fma_f32 v[32:33], v[72:73], 0, v[32:33] op_sel_hi:[1,0,1]
	v_pk_fma_f32 v[30:31], v[76:77], 0, v[30:31] op_sel_hi:[1,0,1]
	v_pk_fma_f32 v[28:29], v[78:79], 0, v[28:29] op_sel_hi:[1,0,1]
	v_pk_fma_f32 v[56:57], v[62:63], 0, v[56:57] op_sel_hi:[1,0,1]
	v_pk_fma_f32 v[58:59], v[60:61], 0, v[58:59] op_sel_hi:[1,0,1]
	v_pk_fma_f32 v[52:53], v[66:67], 0, v[52:53] op_sel_hi:[1,0,1]
	v_pk_fma_f32 v[54:55], v[64:65], 0, v[54:55] op_sel_hi:[1,0,1]
	v_pk_fma_f32 v[32:33], v[72:73], 0, v[32:33] op_sel_hi:[1,0,1]
	v_pk_fma_f32 v[34:35], v[68:69], 0, v[34:35] op_sel_hi:[1,0,1]
	v_pk_fma_f32 v[28:29], v[78:79], 0, v[28:29] op_sel_hi:[1,0,1]
	v_pk_fma_f32 v[30:31], v[76:77], 0, v[30:31] op_sel_hi:[1,0,1]
	v_pk_fma_f32 v[58:59], v[60:61], 0, v[58:59] op_sel_hi:[1,0,1]
	v_pk_fma_f32 v[56:57], v[62:63], 0, v[56:57] op_sel_hi:[1,0,1]
	v_pk_fma_f32 v[54:55], v[64:65], 0, v[54:55] op_sel_hi:[1,0,1]
	v_pk_fma_f32 v[52:53], v[66:67], 0, v[52:53] op_sel_hi:[1,0,1]
	v_pk_fma_f32 v[34:35], v[68:69], 0, v[34:35] op_sel_hi:[1,0,1]
	v_pk_fma_f32 v[32:33], v[72:73], 0, v[32:33] op_sel_hi:[1,0,1]
	v_pk_fma_f32 v[30:31], v[76:77], 0, v[30:31] op_sel_hi:[1,0,1]
	v_pk_fma_f32 v[28:29], v[78:79], 0, v[28:29] op_sel_hi:[1,0,1]
	v_pk_fma_f32 v[56:57], v[62:63], 0, v[56:57] op_sel_hi:[1,0,1]
	v_pk_fma_f32 v[58:59], v[60:61], 0, v[58:59] op_sel_hi:[1,0,1]
	v_pk_fma_f32 v[52:53], v[66:67], 0, v[52:53] op_sel_hi:[1,0,1]
	v_pk_fma_f32 v[54:55], v[64:65], 0, v[54:55] op_sel_hi:[1,0,1]
	v_pk_fma_f32 v[32:33], v[72:73], 0, v[32:33] op_sel_hi:[1,0,1]
	v_pk_fma_f32 v[34:35], v[68:69], 0, v[34:35] op_sel_hi:[1,0,1]
	v_pk_fma_f32 v[28:29], v[78:79], 0, v[28:29] op_sel_hi:[1,0,1]
	v_pk_fma_f32 v[30:31], v[76:77], 0, v[30:31] op_sel_hi:[1,0,1]

; template <int MODE>
; DI void norm_phase(const Args& a, const Frame& F, int nslab, float sscale, float* RSTD, const float* SSP) {
;     ...
;         if (MODE != 1 && nslab > 0) {
; #pragma unroll
;             for (int r = 0; r < RB; ++r) if (rows[r] >= NP) {
; #pragma unroll
;                 for (int hb = 0; hb < 2; ++hb) {
;                     u32x2 t[4][4];
; #pragma unroll
;                     for (int s4 = 0; s4 < 4; ++s4) { const int s = hb * 4 + s4; const u32x2* sp = (const u32x2*)((const bf16*)SL + ((size_t)(s < nslab ? s : 0) * NS + (rows[r] - NP)) * DM);
; #pragma unroll
;                         for (int j = 0; j < 4; ++j) t[s4][j] = sp[F.lane + 64 * j]; }
; #pragma unroll
;                     for (int s4 = 0; s4 < 4; ++s4) { const float wsc = (hb * 4 + s4 < nslab) ? sscale : 0.f;
; #pragma unroll
;                         for (int j = 0; j < 4; ++j) v[r][j] = v[r][j] + (f32x4){bflo(t[s4][j].x), bfhi(t[s4][j].x), bflo(t[s4][j].y), bfhi(t[s4][j].y)} * wsc; }
.LBB0_2217:
	s_waitcnt vmcnt(7)
	v_lshlrev_b32_e32 v50, 16, v42
	v_and_b32_e32 v51, 0xffff0000, v42
	v_lshlrev_b32_e32 v48, 16, v43
	v_and_b32_e32 v49, 0xffff0000, v43
	s_waitcnt vmcnt(6)
	v_lshlrev_b32_e32 v46, 16, v40
	v_and_b32_e32 v47, 0xffff0000, v40
	v_lshlrev_b32_e32 v44, 16, v41
	v_and_b32_e32 v45, 0xffff0000, v41
	s_waitcnt vmcnt(5)
	v_lshlrev_b32_e32 v42, 16, v38
	v_and_b32_e32 v43, 0xffff0000, v38
	v_lshlrev_b32_e32 v40, 16, v39
	v_and_b32_e32 v41, 0xffff0000, v39
	s_waitcnt vmcnt(4)
	v_lshlrev_b32_e32 v38, 16, v36
	v_and_b32_e32 v39, 0xffff0000, v36
	v_lshlrev_b32_e32 v36, 16, v37
	s_cmpk_lt_i32 s12, 0x4000
	v_and_b32_e32 v37, 0xffff0000, v37
	s_cbranch_scc1 .LBB0_2219
	s_cmp_eq_u64 s[14:15], 0
	s_cbranch_scc1 .LBB0_2219
	s_add_i32 s62, s12, 0xffffc000
	s_lshl_b64 s[4:5], s[62:63], 11
	s_add_u32 s4, s77, s4
	s_addc_u32 s5, s66, s5
	v_lshl_add_u64 v[52:53], v[160:161], 3, s[4:5]
	global_load_dwordx2 v[54:55], v[52:53], off
	global_load_dwordx2 v[58:59], v[52:53], off offset:512
	s_waitcnt lgkmcnt(1)
	global_load_dwordx2 v[62:63], v[52:53], off offset:1024
	global_load_dwordx2 v[66:67], v[52:53], off offset:1536
	v_lshl_add_u64 v[56:57], v[52:53], 0, s[82:83]
	v_add_co_u32_e32 v52, vcc, s33, v52
	s_waitcnt vmcnt(1)
	v_lshlrev_b32_e32 v60, 16, v62
	v_addc_co_u32_e32 v53, vcc, 0, v53, vcc
	global_load_dwordx2 v[68:69], v[52:53], off
	global_load_dwordx2 v[70:71], v[56:57], off offset:512
	global_load_dwordx2 v[72:73], v[56:57], off offset:1024
	global_load_dwordx2 v[74:75], v[56:57], off offset:1536
	v_lshlrev_b32_e32 v52, 16, v54
	v_and_b32_e32 v53, 0xffff0000, v54
	v_lshlrev_b32_e32 v54, 16, v55
	v_and_b32_e32 v55, 0xffff0000, v55
	v_pk_add_f32 v[48:49], v[48:49], v[54:55]
	v_lshlrev_b32_e32 v56, 16, v58
	v_and_b32_e32 v57, 0xffff0000, v58
	v_lshlrev_b32_e32 v58, 16, v59
	v_and_b32_e32 v59, 0xffff0000, v59
	v_pk_add_f32 v[46:47], v[46:47], v[56:57]
	v_pk_add_f32 v[44:45], v[44:45], v[58:59]
	s_waitcnt lgkmcnt(0)
	v_and_b32_e32 v61, 0xffff0000, v62
	v_lshlrev_b32_e32 v62, 16, v63
	v_and_b32_e32 v63, 0xffff0000, v63
	v_pk_add_f32 v[42:43], v[42:43], v[60:61]
	v_pk_add_f32 v[40:41], v[40:41], v[62:63]
	s_waitcnt vmcnt(4)
	v_lshlrev_b32_e32 v64, 16, v66
	v_and_b32_e32 v65, 0xffff0000, v66
	v_lshlrev_b32_e32 v66, 16, v67
	v_and_b32_e32 v67, 0xffff0000, v67
	v_pk_add_f32 v[50:51], v[50:51], v[52:53]
	v_pk_add_f32 v[38:39], v[38:39], v[64:65]
	v_pk_add_f32 v[36:37], v[36:37], v[66:67]
	s_waitcnt vmcnt(3)
	v_lshlrev_b32_e32 v82, 16, v68
	v_and_b32_e32 v83, 0xffff0000, v68
	v_lshlrev_b32_e32 v68, 16, v69
	v_and_b32_e32 v69, 0xffff0000, v69
	v_pk_add_f32 v[48:49], v[48:49], v[68:69]
	s_waitcnt vmcnt(2)
	v_lshlrev_b32_e32 v68, 16, v70
	v_and_b32_e32 v69, 0xffff0000, v70
	v_lshlrev_b32_e32 v70, 16, v71
	v_and_b32_e32 v71, 0xffff0000, v71
	v_pk_add_f32 v[44:45], v[44:45], v[70:71]
	v_pk_add_f32 v[46:47], v[46:47], v[68:69]
	s_waitcnt vmcnt(1)
	v_lshlrev_b32_e32 v68, 16, v72
	v_and_b32_e32 v69, 0xffff0000, v72
	v_lshlrev_b32_e32 v70, 16, v73
	v_and_b32_e32 v71, 0xffff0000, v73
	v_pk_add_f32 v[40:41], v[40:41], v[70:71]
	v_pk_add_f32 v[42:43], v[42:43], v[68:69]
	s_waitcnt vmcnt(0)
	v_lshlrev_b32_e32 v68, 16, v74
	v_and_b32_e32 v69, 0xffff0000, v74
	v_lshlrev_b32_e32 v70, 16, v75
	v_and_b32_e32 v71, 0xffff0000, v75
	v_pk_add_f32 v[50:51], v[50:51], v[82:83]
	v_pk_add_f32 v[36:37], v[36:37], v[70:71]
	v_pk_add_f32 v[38:39], v[38:39], v[68:69]
	v_pk_fma_f32 v[50:51], v[52:53], 0, v[50:51] op_sel_hi:[1,0,1]
	v_pk_fma_f32 v[48:49], v[54:55], 0, v[48:49] op_sel_hi:[1,0,1]
	v_pk_fma_f32 v[46:47], v[56:57], 0, v[46:47] op_sel_hi:[1,0,1]
	v_pk_fma_f32 v[44:45], v[58:59], 0, v[44:45] op_sel_hi:[1,0,1]
	v_pk_fma_f32 v[42:43], v[60:61], 0, v[42:43] op_sel_hi:[1,0,1]
	v_pk_fma_f32 v[40:41], v[62:63], 0, v[40:41] op_sel_hi:[1,0,1]
	v_pk_fma_f32 v[38:39], v[64:65], 0, v[38:39] op_sel_hi:[1,0,1]
	v_pk_fma_f32 v[36:37], v[66:67], 0, v[36:37] op_sel_hi:[1,0,1]
	v_pk_fma_f32 v[48:49], v[54:55], 0, v[48:49] op_sel_hi:[1,0,1]
	v_pk_fma_f32 v[50:51], v[52:53], 0, v[50:51] op_sel_hi:[1,0,1]
	v_pk_fma_f32 v[44:45], v[58:59], 0, v[44:45] op_sel_hi:[1,0,1]
	v_pk_fma_f32 v[46:47], v[56:57], 0, v[46:47] op_sel_hi:[1,0,1]
	v_pk_fma_f32 v[40:41], v[62:63], 0, v[40:41] op_sel_hi:[1,0,1]
	v_pk_fma_f32 v[42:43], v[60:61], 0, v[42:43] op_sel_hi:[1,0,1]
	v_pk_fma_f32 v[36:37], v[66:67], 0, v[36:37] op_sel_hi:[1,0,1]
	v_pk_fma_f32 v[38:39], v[64:65], 0, v[38:39] op_sel_hi:[1,0,1]
	v_pk_fma_f32 v[50:51], v[52:53], 0, v[50:51] op_sel_hi:[1,0,1]
	v_pk_fma_f32 v[48:49], v[54:55], 0, v[48:49] op_sel_hi:[1,0,1]
	v_pk_fma_f32 v[46:47], v[56:57], 0, v[46:47] op_sel_hi:[1,0,1]
	v_pk_fma_f32 v[44:45], v[58:59], 0, v[44:45] op_sel_hi:[1,0,1]
	v_pk_fma_f32 v[42:43], v[60:61], 0, v[42:43] op_sel_hi:[1,0,1]
	v_pk_fma_f32 v[40:41], v[62:63], 0, v[40:41] op_sel_hi:[1,0,1]
	v_pk_fma_f32 v[38:39], v[64:65], 0, v[38:39] op_sel_hi:[1,0,1]
	v_pk_fma_f32 v[36:37], v[66:67], 0, v[36:37] op_sel_hi:[1,0,1]
	v_pk_fma_f32 v[48:49], v[54:55], 0, v[48:49] op_sel_hi:[1,0,1]
	v_pk_fma_f32 v[50:51], v[52:53], 0, v[50:51] op_sel_hi:[1,0,1]
	v_pk_fma_f32 v[44:45], v[58:59], 0, v[44:45] op_sel_hi:[1,0,1]
	v_pk_fma_f32 v[46:47], v[56:57], 0, v[46:47] op_sel_hi:[1,0,1]
	v_pk_fma_f32 v[40:41], v[62:63], 0, v[40:41] op_sel_hi:[1,0,1]
	v_pk_fma_f32 v[42:43], v[60:61], 0, v[42:43] op_sel_hi:[1,0,1]
	v_pk_fma_f32 v[36:37], v[66:67], 0, v[36:37] op_sel_hi:[1,0,1]
	v_pk_fma_f32 v[38:39], v[64:65], 0, v[38:39] op_sel_hi:[1,0,1]
	v_pk_fma_f32 v[50:51], v[52:53], 0, v[50:51] op_sel_hi:[1,0,1]
	v_pk_fma_f32 v[48:49], v[54:55], 0, v[48:49] op_sel_hi:[1,0,1]
	v_pk_fma_f32 v[46:47], v[56:57], 0, v[46:47] op_sel_hi:[1,0,1]
	v_pk_fma_f32 v[44:45], v[58:59], 0, v[44:45] op_sel_hi:[1,0,1]
	v_pk_fma_f32 v[42:43], v[60:61], 0, v[42:43] op_sel_hi:[1,0,1]
	v_pk_fma_f32 v[40:41], v[62:63], 0, v[40:41] op_sel_hi:[1,0,1]
	v_pk_fma_f32 v[38:39], v[64:65], 0, v[38:39] op_sel_hi:[1,0,1]
	v_pk_fma_f32 v[36:37], v[66:67], 0, v[36:37] op_sel_hi:[1,0,1]
	v_pk_fma_f32 v[48:49], v[54:55], 0, v[48:49] op_sel_hi:[1,0,1]
	v_pk_fma_f32 v[50:51], v[52:53], 0, v[50:51] op_sel_hi:[1,0,1]
	v_pk_fma_f32 v[44:45], v[58:59], 0, v[44:45] op_sel_hi:[1,0,1]
	v_pk_fma_f32 v[46:47], v[56:57], 0, v[46:47] op_sel_hi:[1,0,1]
	v_pk_fma_f32 v[40:41], v[62:63], 0, v[40:41] op_sel_hi:[1,0,1]
	v_pk_fma_f32 v[42:43], v[60:61], 0, v[42:43] op_sel_hi:[1,0,1]
	v_pk_fma_f32 v[36:37], v[66:67], 0, v[36:37] op_sel_hi:[1,0,1]
	v_pk_fma_f32 v[38:39], v[64:65], 0, v[38:39] op_sel_hi:[1,0,1]
; template <int MODE>
; DI void norm_phase(const Args& a, const Frame& F, int nslab, float sscale, float* RSTD, const float* SSP) {
;     ...
;         if (MODE != 1 && nslab > 0) {
; #pragma unroll
;             for (int r = 0; r < RB; ++r) if (rows[r] >= NP) {
; #pragma unroll
;                 for (int hb = 0; hb < 2; ++hb) {
;                     u32x2 t[4][4];
; #pragma unroll
;                     for (int s4 = 0; s4 < 4; ++s4) { const int s = hb * 4 + s4; const u32x2* sp = (const u32x2*)((const bf16*)SL + ((size_t)(s < nslab ? s : 0) * NS + (rows[r] - NP)) * DM);
; #pragma unroll
;                         for (int j = 0; j < 4; ++j) t[s4][j] = sp[F.lane + 64 * j]; }
; #pragma unroll
;                     for (int s4 = 0; s4 < 4; ++s4) { const float wsc = (hb * 4 + s4 < nslab) ? sscale : 0.f;
; #pragma unroll
;                         for (int j = 0; j < 4; ++j) v[r][j] = v[r][j] + (f32x4){bflo(t[s4][j].x), bfhi(t[s4][j].x), bflo(t[s4][j].y), bfhi(t[s4][j].y)} * wsc; }
.LBB0_2219:
	s_waitcnt vmcnt(3)
	v_lshlrev_b32_e32 v58, 16, v34
	v_and_b32_e32 v59, 0xffff0000, v34
	v_lshlrev_b32_e32 v56, 16, v35
	v_and_b32_e32 v57, 0xffff0000, v35
	s_waitcnt vmcnt(2)
	v_lshlrev_b32_e32 v54, 16, v32
	v_and_b32_e32 v55, 0xffff0000, v32
	v_lshlrev_b32_e32 v52, 16, v33
	v_and_b32_e32 v53, 0xffff0000, v33
	s_waitcnt vmcnt(1)
	v_lshlrev_b32_e32 v34, 16, v30
	v_and_b32_e32 v35, 0xffff0000, v30
	v_lshlrev_b32_e32 v32, 16, v31
	v_and_b32_e32 v33, 0xffff0000, v31
	s_waitcnt vmcnt(0)
	v_lshlrev_b32_e32 v30, 16, v28
	v_and_b32_e32 v31, 0xffff0000, v28
	v_lshlrev_b32_e32 v28, 16, v29
	s_cmpk_lt_i32 s8, 0x4000
	v_and_b32_e32 v29, 0xffff0000, v29
	s_cbranch_scc1 .LBB0_2221
	s_cmp_eq_u64 s[10:11], 0
	s_cbranch_scc1 .LBB0_2221
	s_add_i32 s62, s8, 0xffffc000
	s_lshl_b64 s[4:5], s[62:63], 11
	s_add_u32 s4, s77, s4
	s_addc_u32 s5, s66, s5
	s_waitcnt lgkmcnt(0)
	v_lshl_add_u64 v[60:61], v[160:161], 3, s[4:5]
	global_load_dwordx2 v[62:63], v[60:61], off
	global_load_dwordx2 v[66:67], v[60:61], off offset:512
	global_load_dwordx2 v[70:71], v[60:61], off offset:1024
	global_load_dwordx2 v[74:75], v[60:61], off offset:1536
	v_lshl_add_u64 v[64:65], v[60:61], 0, s[82:83]
	v_add_co_u32_e32 v60, vcc, s33, v60
	s_waitcnt vmcnt(1)
	v_lshlrev_b32_e32 v68, 16, v70
	v_addc_co_u32_e32 v61, vcc, 0, v61, vcc
	global_load_dwordx2 v[82:83], v[60:61], off
	global_load_dwordx2 v[84:85], v[64:65], off offset:512
	global_load_dwordx2 v[86:87], v[64:65], off offset:1024
	global_load_dwordx2 v[88:89], v[64:65], off offset:1536
	v_lshlrev_b32_e32 v60, 16, v62
	v_and_b32_e32 v61, 0xffff0000, v62
	v_lshlrev_b32_e32 v62, 16, v63
	v_and_b32_e32 v63, 0xffff0000, v63
	v_pk_add_f32 v[56:57], v[56:57], v[62:63]
	v_lshlrev_b32_e32 v64, 16, v66
	v_and_b32_e32 v65, 0xffff0000, v66
	v_lshlrev_b32_e32 v66, 16, v67
	v_and_b32_e32 v67, 0xffff0000, v67
	v_pk_add_f32 v[54:55], v[54:55], v[64:65]
	v_pk_add_f32 v[52:53], v[52:53], v[66:67]
	v_and_b32_e32 v69, 0xffff0000, v70
	v_lshlrev_b32_e32 v70, 16, v71
	v_and_b32_e32 v71, 0xffff0000, v71
	v_pk_add_f32 v[34:35], v[34:35], v[68:69]
	v_pk_add_f32 v[32:33], v[32:33], v[70:71]
	s_waitcnt vmcnt(4)
	v_lshlrev_b32_e32 v72, 16, v74
	v_and_b32_e32 v73, 0xffff0000, v74
	v_lshlrev_b32_e32 v74, 16, v75
	v_and_b32_e32 v75, 0xffff0000, v75
	v_pk_add_f32 v[58:59], v[58:59], v[60:61]
	v_pk_add_f32 v[30:31], v[30:31], v[72:73]
	v_pk_add_f32 v[28:29], v[28:29], v[74:75]
	s_waitcnt vmcnt(3)
	v_lshlrev_b32_e32 v90, 16, v82
	v_and_b32_e32 v91, 0xffff0000, v82
	v_lshlrev_b32_e32 v82, 16, v83
	v_and_b32_e32 v83, 0xffff0000, v83
	v_pk_add_f32 v[56:57], v[56:57], v[82:83]
	s_waitcnt vmcnt(2)
	v_lshlrev_b32_e32 v82, 16, v84
	v_and_b32_e32 v83, 0xffff0000, v84
	v_lshlrev_b32_e32 v84, 16, v85
	v_and_b32_e32 v85, 0xffff0000, v85
	v_pk_add_f32 v[52:53], v[52:53], v[84:85]
	v_pk_add_f32 v[54:55], v[54:55], v[82:83]
	s_waitcnt vmcnt(1)
	v_lshlrev_b32_e32 v82, 16, v86
	v_and_b32_e32 v83, 0xffff0000, v86
	v_lshlrev_b32_e32 v84, 16, v87
	v_and_b32_e32 v85, 0xffff0000, v87
	v_pk_add_f32 v[32:33], v[32:33], v[84:85]
	v_pk_add_f32 v[34:35], v[34:35], v[82:83]
	s_waitcnt vmcnt(0)
	v_lshlrev_b32_e32 v82, 16, v88
	v_and_b32_e32 v83, 0xffff0000, v88
	v_lshlrev_b32_e32 v84, 16, v89
	v_and_b32_e32 v85, 0xffff0000, v89
	v_pk_add_f32 v[58:59], v[58:59], v[90:91]
	v_pk_add_f32 v[28:29], v[28:29], v[84:85]
	v_pk_add_f32 v[30:31], v[30:31], v[82:83]
	v_pk_fma_f32 v[58:59], v[60:61], 0, v[58:59] op_sel_hi:[1,0,1]
	v_pk_fma_f32 v[56:57], v[62:63], 0, v[56:57] op_sel_hi:[1,0,1]
	v_pk_fma_f32 v[54:55], v[64:65], 0, v[54:55] op_sel_hi:[1,0,1]
	v_pk_fma_f32 v[52:53], v[66:67], 0, v[52:53] op_sel_hi:[1,0,1]
	v_pk_fma_f32 v[34:35], v[68:69], 0, v[34:35] op_sel_hi:[1,0,1]
	v_pk_fma_f32 v[32:33], v[70:71], 0, v[32:33] op_sel_hi:[1,0,1]
	v_pk_fma_f32 v[30:31], v[72:73], 0, v[30:31] op_sel_hi:[1,0,1]
	v_pk_fma_f32 v[28:29], v[74:75], 0, v[28:29] op_sel_hi:[1,0,1]
	v_pk_fma_f32 v[56:57], v[62:63], 0, v[56:57] op_sel_hi:[1,0,1]
	v_pk_fma_f32 v[58:59], v[60:61], 0, v[58:59] op_sel_hi:[1,0,1]
	v_pk_fma_f32 v[52:53], v[66:67], 0, v[52:53] op_sel_hi:[1,0,1]
	v_pk_fma_f32 v[54:55], v[64:65], 0, v[54:55] op_sel_hi:[1,0,1]
	v_pk_fma_f32 v[32:33], v[70:71], 0, v[32:33] op_sel_hi:[1,0,1]
	v_pk_fma_f32 v[34:35], v[68:69], 0, v[34:35] op_sel_hi:[1,0,1]
	v_pk_fma_f32 v[28:29], v[74:75], 0, v[28:29] op_sel_hi:[1,0,1]
	v_pk_fma_f32 v[30:31], v[72:73], 0, v[30:31] op_sel_hi:[1,0,1]
	v_pk_fma_f32 v[58:59], v[60:61], 0, v[58:59] op_sel_hi:[1,0,1]
	v_pk_fma_f32 v[56:57], v[62:63], 0, v[56:57] op_sel_hi:[1,0,1]
	v_pk_fma_f32 v[54:55], v[64:65], 0, v[54:55] op_sel_hi:[1,0,1]
	v_pk_fma_f32 v[52:53], v[66:67], 0, v[52:53] op_sel_hi:[1,0,1]
	v_pk_fma_f32 v[34:35], v[68:69], 0, v[34:35] op_sel_hi:[1,0,1]
	v_pk_fma_f32 v[32:33], v[70:71], 0, v[32:33] op_sel_hi:[1,0,1]
	v_pk_fma_f32 v[30:31], v[72:73], 0, v[30:31] op_sel_hi:[1,0,1]
	v_pk_fma_f32 v[28:29], v[74:75], 0, v[28:29] op_sel_hi:[1,0,1]
	v_pk_fma_f32 v[56:57], v[62:63], 0, v[56:57] op_sel_hi:[1,0,1]
	v_pk_fma_f32 v[58:59], v[60:61], 0, v[58:59] op_sel_hi:[1,0,1]
	v_pk_fma_f32 v[52:53], v[66:67], 0, v[52:53] op_sel_hi:[1,0,1]
	v_pk_fma_f32 v[54:55], v[64:65], 0, v[54:55] op_sel_hi:[1,0,1]
	v_pk_fma_f32 v[32:33], v[70:71], 0, v[32:33] op_sel_hi:[1,0,1]
	v_pk_fma_f32 v[34:35], v[68:69], 0, v[34:35] op_sel_hi:[1,0,1]
	v_pk_fma_f32 v[28:29], v[74:75], 0, v[28:29] op_sel_hi:[1,0,1]
	v_pk_fma_f32 v[30:31], v[72:73], 0, v[30:31] op_sel_hi:[1,0,1]
	v_pk_fma_f32 v[58:59], v[60:61], 0, v[58:59] op_sel_hi:[1,0,1]
	v_pk_fma_f32 v[56:57], v[62:63], 0, v[56:57] op_sel_hi:[1,0,1]
	v_pk_fma_f32 v[54:55], v[64:65], 0, v[54:55] op_sel_hi:[1,0,1]
	v_pk_fma_f32 v[52:53], v[66:67], 0, v[52:53] op_sel_hi:[1,0,1]
	v_pk_fma_f32 v[34:35], v[68:69], 0, v[34:35] op_sel_hi:[1,0,1]
	v_pk_fma_f32 v[32:33], v[70:71], 0, v[32:33] op_sel_hi:[1,0,1]
	v_pk_fma_f32 v[30:31], v[72:73], 0, v[30:31] op_sel_hi:[1,0,1]
	v_pk_fma_f32 v[28:29], v[74:75], 0, v[28:29] op_sel_hi:[1,0,1]
	v_pk_fma_f32 v[56:57], v[62:63], 0, v[56:57] op_sel_hi:[1,0,1]
	v_pk_fma_f32 v[58:59], v[60:61], 0, v[58:59] op_sel_hi:[1,0,1]
	v_pk_fma_f32 v[52:53], v[66:67], 0, v[52:53] op_sel_hi:[1,0,1]
	v_pk_fma_f32 v[54:55], v[64:65], 0, v[54:55] op_sel_hi:[1,0,1]
	v_pk_fma_f32 v[32:33], v[70:71], 0, v[32:33] op_sel_hi:[1,0,1]
	v_pk_fma_f32 v[34:35], v[68:69], 0, v[34:35] op_sel_hi:[1,0,1]
	v_pk_fma_f32 v[28:29], v[74:75], 0, v[28:29] op_sel_hi:[1,0,1]
	v_pk_fma_f32 v[30:31], v[72:73], 0, v[30:31] op_sel_hi:[1,0,1]
